# gemm_in: straight-line epilogues for single-class tiles (plain PROJ columns: 32 packed 8-byte stores off one SGPR base; ctx k_a/k_d tiles: plus the f32 nt cache stores); other tiles keep the original
# speedup vs baseline: 1.0422x; 1.0214x over previous
.Lgin_loop:
	s_waitcnt vmcnt(4)
	s_barrier
	ds_read_b128 v[230:233], v175 offset:0
	ds_read_b128 v[234:237], v175 offset:2048
	ds_read_b128 v[238:241], v175 offset:4096
	ds_read_b128 v[242:245], v175 offset:6144
	ds_read_b128 v[136:139], v177 offset:0
	ds_read_b128 v[140:143], v177 offset:2048
	ds_read_b128 v[144:147], v177 offset:4096
	ds_read_b128 v[148:151], v177 offset:6144
	ds_read_b128 v[182:185], v176 offset:16384
	ds_read_b128 v[186:189], v176 offset:18432
	ds_read_b128 v[190:193], v176 offset:20480
	ds_read_b128 v[194:197], v176 offset:22528
	s_add_u32 m0, s11, 0xc000
	s_waitcnt lgkmcnt(3)
	v_mfma_f32_16x16x32_f16 v[124:127], v[230:233], v[182:185], v[124:127]
	v_mfma_f32_16x16x32_f16 v[92:95], v[234:237], v[182:185], v[92:95]
	v_mfma_f32_16x16x32_f16 v[60:63], v[238:241], v[182:185], v[60:63]
	v_mfma_f32_16x16x32_f16 v[28:31], v[242:245], v[182:185], v[28:31]
	global_load_lds_dwordx4 v128, s[6:7]
	s_barrier
	ds_read_b128 v[198:201], v178 offset:16384
	ds_read_b128 v[202:205], v178 offset:18432
	ds_read_b128 v[222:225], v178 offset:20480
	ds_read_b128 v[226:229], v178 offset:22528
	s_add_u32 m0, s11, 0xd000
	s_waitcnt lgkmcnt(6)
	v_mfma_f32_16x16x32_f16 v[120:123], v[230:233], v[186:189], v[120:123]
	v_mfma_f32_16x16x32_f16 v[88:91], v[234:237], v[186:189], v[88:91]
	v_mfma_f32_16x16x32_f16 v[56:59], v[238:241], v[186:189], v[56:59]
	v_mfma_f32_16x16x32_f16 v[24:27], v[242:245], v[186:189], v[24:27]
	global_load_lds_dwordx4 v129, s[6:7]
	s_add_u32 m0, s11, 0xe000
	s_waitcnt lgkmcnt(5)
	v_mfma_f32_16x16x32_f16 v[116:119], v[230:233], v[190:193], v[116:119]
	v_mfma_f32_16x16x32_f16 v[84:87], v[234:237], v[190:193], v[84:87]
	v_mfma_f32_16x16x32_f16 v[52:55], v[238:241], v[190:193], v[52:55]
	v_mfma_f32_16x16x32_f16 v[20:23], v[242:245], v[190:193], v[20:23]
	global_load_lds_dwordx4 v132, s[6:7]
	s_add_u32 m0, s11, 0xf000
	s_waitcnt lgkmcnt(4)
	v_mfma_f32_16x16x32_f16 v[112:115], v[230:233], v[194:197], v[112:115]
	v_mfma_f32_16x16x32_f16 v[80:83], v[234:237], v[194:197], v[80:83]
	v_mfma_f32_16x16x32_f16 v[48:51], v[238:241], v[194:197], v[48:51]
	v_mfma_f32_16x16x32_f16 v[16:19], v[242:245], v[194:197], v[16:19]
	global_load_lds_dwordx4 v133, s[6:7]
	s_add_u32 m0, s11, 0x0
	s_waitcnt lgkmcnt(3)
	v_mfma_f32_16x16x32_f16 v[124:127], v[136:139], v[198:201], v[124:127]
	v_mfma_f32_16x16x32_f16 v[92:95], v[140:143], v[198:201], v[92:95]
	v_mfma_f32_16x16x32_f16 v[60:63], v[144:147], v[198:201], v[60:63]
	v_mfma_f32_16x16x32_f16 v[28:31], v[148:151], v[198:201], v[28:31]
	global_load_lds_dwordx4 v128, s[4:5]
	s_add_u32 m0, s11, 0x1000
	s_waitcnt lgkmcnt(2)
	v_mfma_f32_16x16x32_f16 v[120:123], v[136:139], v[202:205], v[120:123]
	v_mfma_f32_16x16x32_f16 v[88:91], v[140:143], v[202:205], v[88:91]
	v_mfma_f32_16x16x32_f16 v[56:59], v[144:147], v[202:205], v[56:59]
	v_mfma_f32_16x16x32_f16 v[24:27], v[148:151], v[202:205], v[24:27]
	global_load_lds_dwordx4 v129, s[4:5]
	s_add_u32 m0, s11, 0x2000
	s_waitcnt lgkmcnt(1)
	v_mfma_f32_16x16x32_f16 v[116:119], v[136:139], v[222:225], v[116:119]
	v_mfma_f32_16x16x32_f16 v[84:87], v[140:143], v[222:225], v[84:87]
	v_mfma_f32_16x16x32_f16 v[52:55], v[144:147], v[222:225], v[52:55]
	v_mfma_f32_16x16x32_f16 v[20:23], v[148:151], v[222:225], v[20:23]
	global_load_lds_dwordx4 v130, s[4:5]
	s_add_u32 m0, s11, 0x3000
	s_waitcnt lgkmcnt(0)
	v_mfma_f32_16x16x32_f16 v[112:115], v[136:139], v[226:229], v[112:115]
	v_mfma_f32_16x16x32_f16 v[80:83], v[140:143], v[226:229], v[80:83]
	v_mfma_f32_16x16x32_f16 v[48:51], v[144:147], v[226:229], v[48:51]
	v_mfma_f32_16x16x32_f16 v[16:19], v[148:151], v[226:229], v[16:19]
	global_load_lds_dwordx4 v131, s[4:5]
	s_add_u32 s6, s6, 128
	s_addc_u32 s7, s7, 0
	s_add_u32 s4, s4, 128
	s_addc_u32 s5, s5, 0
	s_waitcnt vmcnt(8)
	s_barrier
	ds_read_b128 v[182:185], v176 offset:32768
	ds_read_b128 v[186:189], v176 offset:34816
	ds_read_b128 v[190:193], v176 offset:36864
	ds_read_b128 v[194:197], v176 offset:38912
	ds_read_b128 v[198:201], v178 offset:32768
	ds_read_b128 v[202:205], v178 offset:34816
	ds_read_b128 v[222:225], v178 offset:36864
	ds_read_b128 v[226:229], v178 offset:38912
	s_add_u32 m0, s11, 0x4000
	s_waitcnt lgkmcnt(7)
	v_mfma_f32_16x16x32_f16 v[108:111], v[230:233], v[182:185], v[108:111]
	v_mfma_f32_16x16x32_f16 v[76:79], v[234:237], v[182:185], v[76:79]
	v_mfma_f32_16x16x32_f16 v[44:47], v[238:241], v[182:185], v[44:47]
	v_mfma_f32_16x16x32_f16 v[12:15], v[242:245], v[182:185], v[12:15]
	global_load_lds_dwordx4 v128, s[18:19]
	s_add_u32 m0, s11, 0x5000
	s_waitcnt lgkmcnt(6)
	v_mfma_f32_16x16x32_f16 v[104:107], v[230:233], v[186:189], v[104:107]
	v_mfma_f32_16x16x32_f16 v[72:75], v[234:237], v[186:189], v[72:75]
	v_mfma_f32_16x16x32_f16 v[40:43], v[238:241], v[186:189], v[40:43]
	v_mfma_f32_16x16x32_f16 v[8:11], v[242:245], v[186:189], v[8:11]
	global_load_lds_dwordx4 v129, s[18:19]
	s_add_u32 m0, s11, 0x6000
	s_waitcnt lgkmcnt(5)
	v_mfma_f32_16x16x32_f16 v[100:103], v[230:233], v[190:193], v[100:103]
	v_mfma_f32_16x16x32_f16 v[68:71], v[234:237], v[190:193], v[68:71]
	v_mfma_f32_16x16x32_f16 v[36:39], v[238:241], v[190:193], v[36:39]
	v_mfma_f32_16x16x32_f16 v[4:7], v[242:245], v[190:193], v[4:7]
	global_load_lds_dwordx4 v132, s[18:19]
	s_add_u32 m0, s11, 0x7000
	s_waitcnt lgkmcnt(4)
	v_mfma_f32_16x16x32_f16 v[96:99], v[230:233], v[194:197], v[96:99]
	v_mfma_f32_16x16x32_f16 v[64:67], v[234:237], v[194:197], v[64:67]
	v_mfma_f32_16x16x32_f16 v[32:35], v[238:241], v[194:197], v[32:35]
	v_mfma_f32_16x16x32_f16 v[0:3], v[242:245], v[194:197], v[0:3]
	global_load_lds_dwordx4 v133, s[18:19]
	s_waitcnt lgkmcnt(3)
	v_mfma_f32_16x16x32_f16 v[108:111], v[136:139], v[198:201], v[108:111]
	v_mfma_f32_16x16x32_f16 v[76:79], v[140:143], v[198:201], v[76:79]
	v_mfma_f32_16x16x32_f16 v[44:47], v[144:147], v[198:201], v[44:47]
	v_mfma_f32_16x16x32_f16 v[12:15], v[148:151], v[198:201], v[12:15]
	s_waitcnt lgkmcnt(2)
	v_mfma_f32_16x16x32_f16 v[104:107], v[136:139], v[202:205], v[104:107]
	v_mfma_f32_16x16x32_f16 v[72:75], v[140:143], v[202:205], v[72:75]
	v_mfma_f32_16x16x32_f16 v[40:43], v[144:147], v[202:205], v[40:43]
	v_mfma_f32_16x16x32_f16 v[8:11], v[148:151], v[202:205], v[8:11]
	s_waitcnt lgkmcnt(1)
	v_mfma_f32_16x16x32_f16 v[100:103], v[136:139], v[222:225], v[100:103]
	v_mfma_f32_16x16x32_f16 v[68:71], v[140:143], v[222:225], v[68:71]
	v_mfma_f32_16x16x32_f16 v[36:39], v[144:147], v[222:225], v[36:39]
	v_mfma_f32_16x16x32_f16 v[4:7], v[148:151], v[222:225], v[4:7]
	s_waitcnt lgkmcnt(0)
	v_mfma_f32_16x16x32_f16 v[96:99], v[136:139], v[226:229], v[96:99]
	v_mfma_f32_16x16x32_f16 v[64:67], v[140:143], v[226:229], v[64:67]
	v_mfma_f32_16x16x32_f16 v[32:35], v[144:147], v[226:229], v[32:35]
	v_mfma_f32_16x16x32_f16 v[0:3], v[148:151], v[226:229], v[0:3]
	s_add_u32 s18, s18, 128
	s_addc_u32 s19, s19, 0
	s_waitcnt vmcnt(4)
	s_barrier
	ds_read_b128 v[230:233], v175 offset:0
	ds_read_b128 v[234:237], v175 offset:2048
	ds_read_b128 v[238:241], v175 offset:4096
	ds_read_b128 v[242:245], v175 offset:6144
	ds_read_b128 v[136:139], v177 offset:0
	ds_read_b128 v[140:143], v177 offset:2048
	ds_read_b128 v[144:147], v177 offset:4096
	ds_read_b128 v[148:151], v177 offset:6144
	ds_read_b128 v[182:185], v176 offset:49152
	ds_read_b128 v[186:189], v176 offset:51200
	ds_read_b128 v[190:193], v176 offset:53248
	ds_read_b128 v[194:197], v176 offset:55296
	s_add_u32 m0, s11, 0x8000
	s_waitcnt lgkmcnt(3)
	v_mfma_f32_16x16x32_f16 v[124:127], v[230:233], v[182:185], v[124:127]
	v_mfma_f32_16x16x32_f16 v[92:95], v[234:237], v[182:185], v[92:95]
	v_mfma_f32_16x16x32_f16 v[60:63], v[238:241], v[182:185], v[60:63]
	v_mfma_f32_16x16x32_f16 v[28:31], v[242:245], v[182:185], v[28:31]
	global_load_lds_dwordx4 v128, s[6:7]
	s_barrier
	ds_read_b128 v[198:201], v178 offset:49152
	ds_read_b128 v[202:205], v178 offset:51200
	ds_read_b128 v[222:225], v178 offset:53248
	ds_read_b128 v[226:229], v178 offset:55296
	s_add_u32 m0, s11, 0x9000
	s_waitcnt lgkmcnt(6)
	v_mfma_f32_16x16x32_f16 v[120:123], v[230:233], v[186:189], v[120:123]
	v_mfma_f32_16x16x32_f16 v[88:91], v[234:237], v[186:189], v[88:91]
	v_mfma_f32_16x16x32_f16 v[56:59], v[238:241], v[186:189], v[56:59]
	v_mfma_f32_16x16x32_f16 v[24:27], v[242:245], v[186:189], v[24:27]
	global_load_lds_dwordx4 v129, s[6:7]
	s_add_u32 m0, s11, 0xa000
	s_waitcnt lgkmcnt(5)
	v_mfma_f32_16x16x32_f16 v[116:119], v[230:233], v[190:193], v[116:119]
	v_mfma_f32_16x16x32_f16 v[84:87], v[234:237], v[190:193], v[84:87]
	v_mfma_f32_16x16x32_f16 v[52:55], v[238:241], v[190:193], v[52:55]
	v_mfma_f32_16x16x32_f16 v[20:23], v[242:245], v[190:193], v[20:23]
	global_load_lds_dwordx4 v132, s[6:7]
	s_add_u32 m0, s11, 0xb000
	s_waitcnt lgkmcnt(4)
	v_mfma_f32_16x16x32_f16 v[112:115], v[230:233], v[194:197], v[112:115]
	v_mfma_f32_16x16x32_f16 v[80:83], v[234:237], v[194:197], v[80:83]
	v_mfma_f32_16x16x32_f16 v[48:51], v[238:241], v[194:197], v[48:51]
	v_mfma_f32_16x16x32_f16 v[16:19], v[242:245], v[194:197], v[16:19]
	global_load_lds_dwordx4 v133, s[6:7]
	s_add_u32 m0, s11, 0x0
	s_waitcnt lgkmcnt(3)
	v_mfma_f32_16x16x32_f16 v[124:127], v[136:139], v[198:201], v[124:127]
	v_mfma_f32_16x16x32_f16 v[92:95], v[140:143], v[198:201], v[92:95]
	v_mfma_f32_16x16x32_f16 v[60:63], v[144:147], v[198:201], v[60:63]
	v_mfma_f32_16x16x32_f16 v[28:31], v[148:151], v[198:201], v[28:31]
	global_load_lds_dwordx4 v128, s[4:5]
	s_add_u32 m0, s11, 0x1000
	s_waitcnt lgkmcnt(2)
	v_mfma_f32_16x16x32_f16 v[120:123], v[136:139], v[202:205], v[120:123]
	v_mfma_f32_16x16x32_f16 v[88:91], v[140:143], v[202:205], v[88:91]
	v_mfma_f32_16x16x32_f16 v[56:59], v[144:147], v[202:205], v[56:59]
	v_mfma_f32_16x16x32_f16 v[24:27], v[148:151], v[202:205], v[24:27]
	global_load_lds_dwordx4 v129, s[4:5]
	s_add_u32 m0, s11, 0x2000
	s_waitcnt lgkmcnt(1)
	v_mfma_f32_16x16x32_f16 v[116:119], v[136:139], v[222:225], v[116:119]
	v_mfma_f32_16x16x32_f16 v[84:87], v[140:143], v[222:225], v[84:87]
	v_mfma_f32_16x16x32_f16 v[52:55], v[144:147], v[222:225], v[52:55]
	v_mfma_f32_16x16x32_f16 v[20:23], v[148:151], v[222:225], v[20:23]
	global_load_lds_dwordx4 v130, s[4:5]
	s_add_u32 m0, s11, 0x3000
	s_waitcnt lgkmcnt(0)
	v_mfma_f32_16x16x32_f16 v[112:115], v[136:139], v[226:229], v[112:115]
	v_mfma_f32_16x16x32_f16 v[80:83], v[140:143], v[226:229], v[80:83]
	v_mfma_f32_16x16x32_f16 v[48:51], v[144:147], v[226:229], v[48:51]
	v_mfma_f32_16x16x32_f16 v[16:19], v[148:151], v[226:229], v[16:19]
	global_load_lds_dwordx4 v131, s[4:5]
	s_add_u32 s6, s6, 128
	s_addc_u32 s7, s7, 0
	s_add_u32 s4, s4, 128
	s_addc_u32 s5, s5, 0
	s_waitcnt vmcnt(8)
	s_barrier
	ds_read_b128 v[182:185], v176 offset:16384
	ds_read_b128 v[186:189], v176 offset:18432
	ds_read_b128 v[190:193], v176 offset:20480
	ds_read_b128 v[194:197], v176 offset:22528
	ds_read_b128 v[198:201], v178 offset:16384
	ds_read_b128 v[202:205], v178 offset:18432
	ds_read_b128 v[222:225], v178 offset:20480
	ds_read_b128 v[226:229], v178 offset:22528
	s_add_u32 m0, s11, 0xc000
	s_waitcnt lgkmcnt(7)
	v_mfma_f32_16x16x32_f16 v[108:111], v[230:233], v[182:185], v[108:111]
	v_mfma_f32_16x16x32_f16 v[76:79], v[234:237], v[182:185], v[76:79]
	v_mfma_f32_16x16x32_f16 v[44:47], v[238:241], v[182:185], v[44:47]
	v_mfma_f32_16x16x32_f16 v[12:15], v[242:245], v[182:185], v[12:15]
	global_load_lds_dwordx4 v128, s[18:19]
	s_add_u32 m0, s11, 0xd000
	s_waitcnt lgkmcnt(6)
	v_mfma_f32_16x16x32_f16 v[104:107], v[230:233], v[186:189], v[104:107]
	v_mfma_f32_16x16x32_f16 v[72:75], v[234:237], v[186:189], v[72:75]
	v_mfma_f32_16x16x32_f16 v[40:43], v[238:241], v[186:189], v[40:43]
	v_mfma_f32_16x16x32_f16 v[8:11], v[242:245], v[186:189], v[8:11]
	global_load_lds_dwordx4 v129, s[18:19]
	s_add_u32 m0, s11, 0xe000
	s_waitcnt lgkmcnt(5)
	v_mfma_f32_16x16x32_f16 v[100:103], v[230:233], v[190:193], v[100:103]
	v_mfma_f32_16x16x32_f16 v[68:71], v[234:237], v[190:193], v[68:71]
	v_mfma_f32_16x16x32_f16 v[36:39], v[238:241], v[190:193], v[36:39]
	v_mfma_f32_16x16x32_f16 v[4:7], v[242:245], v[190:193], v[4:7]
	global_load_lds_dwordx4 v132, s[18:19]
	s_add_u32 m0, s11, 0xf000
	s_waitcnt lgkmcnt(4)
	v_mfma_f32_16x16x32_f16 v[96:99], v[230:233], v[194:197], v[96:99]
	v_mfma_f32_16x16x32_f16 v[64:67], v[234:237], v[194:197], v[64:67]
	v_mfma_f32_16x16x32_f16 v[32:35], v[238:241], v[194:197], v[32:35]
	v_mfma_f32_16x16x32_f16 v[0:3], v[242:245], v[194:197], v[0:3]
	global_load_lds_dwordx4 v133, s[18:19]
	s_waitcnt lgkmcnt(3)
	v_mfma_f32_16x16x32_f16 v[108:111], v[136:139], v[198:201], v[108:111]
	v_mfma_f32_16x16x32_f16 v[76:79], v[140:143], v[198:201], v[76:79]
	v_mfma_f32_16x16x32_f16 v[44:47], v[144:147], v[198:201], v[44:47]
	v_mfma_f32_16x16x32_f16 v[12:15], v[148:151], v[198:201], v[12:15]
	s_waitcnt lgkmcnt(2)
	v_mfma_f32_16x16x32_f16 v[104:107], v[136:139], v[202:205], v[104:107]
	v_mfma_f32_16x16x32_f16 v[72:75], v[140:143], v[202:205], v[72:75]
	v_mfma_f32_16x16x32_f16 v[40:43], v[144:147], v[202:205], v[40:43]
	v_mfma_f32_16x16x32_f16 v[8:11], v[148:151], v[202:205], v[8:11]
	s_waitcnt lgkmcnt(1)
	v_mfma_f32_16x16x32_f16 v[100:103], v[136:139], v[222:225], v[100:103]
	v_mfma_f32_16x16x32_f16 v[68:71], v[140:143], v[222:225], v[68:71]
	v_mfma_f32_16x16x32_f16 v[36:39], v[144:147], v[222:225], v[36:39]
	v_mfma_f32_16x16x32_f16 v[4:7], v[148:151], v[222:225], v[4:7]
	s_waitcnt lgkmcnt(0)
	v_mfma_f32_16x16x32_f16 v[96:99], v[136:139], v[226:229], v[96:99]
	v_mfma_f32_16x16x32_f16 v[64:67], v[140:143], v[226:229], v[64:67]
	v_mfma_f32_16x16x32_f16 v[32:35], v[144:147], v[226:229], v[32:35]
	v_mfma_f32_16x16x32_f16 v[0:3], v[148:151], v[226:229], v[0:3]
	s_add_u32 s18, s18, 128
	s_addc_u32 s19, s19, 0
	s_waitcnt vmcnt(4)
	s_barrier
	ds_read_b128 v[230:233], v175 offset:0
	ds_read_b128 v[234:237], v175 offset:2048
	ds_read_b128 v[238:241], v175 offset:4096
	ds_read_b128 v[242:245], v175 offset:6144
	ds_read_b128 v[136:139], v177 offset:0
	ds_read_b128 v[140:143], v177 offset:2048
	ds_read_b128 v[144:147], v177 offset:4096
	ds_read_b128 v[148:151], v177 offset:6144
	ds_read_b128 v[182:185], v176 offset:32768
	ds_read_b128 v[186:189], v176 offset:34816
	ds_read_b128 v[190:193], v176 offset:36864
	ds_read_b128 v[194:197], v176 offset:38912
	s_add_u32 m0, s11, 0x4000
	s_waitcnt lgkmcnt(3)
	v_mfma_f32_16x16x32_f16 v[124:127], v[230:233], v[182:185], v[124:127]
	v_mfma_f32_16x16x32_f16 v[92:95], v[234:237], v[182:185], v[92:95]
	v_mfma_f32_16x16x32_f16 v[60:63], v[238:241], v[182:185], v[60:63]
	v_mfma_f32_16x16x32_f16 v[28:31], v[242:245], v[182:185], v[28:31]
	global_load_lds_dwordx4 v128, s[6:7]
	s_barrier
	ds_read_b128 v[198:201], v178 offset:32768
	ds_read_b128 v[202:205], v178 offset:34816
	ds_read_b128 v[222:225], v178 offset:36864
	ds_read_b128 v[226:229], v178 offset:38912
	s_add_u32 m0, s11, 0x5000
	s_waitcnt lgkmcnt(6)
	v_mfma_f32_16x16x32_f16 v[120:123], v[230:233], v[186:189], v[120:123]
	v_mfma_f32_16x16x32_f16 v[88:91], v[234:237], v[186:189], v[88:91]
	v_mfma_f32_16x16x32_f16 v[56:59], v[238:241], v[186:189], v[56:59]
	v_mfma_f32_16x16x32_f16 v[24:27], v[242:245], v[186:189], v[24:27]
	global_load_lds_dwordx4 v129, s[6:7]
	s_add_u32 m0, s11, 0x6000
	s_waitcnt lgkmcnt(5)
	v_mfma_f32_16x16x32_f16 v[116:119], v[230:233], v[190:193], v[116:119]
	v_mfma_f32_16x16x32_f16 v[84:87], v[234:237], v[190:193], v[84:87]
	v_mfma_f32_16x16x32_f16 v[52:55], v[238:241], v[190:193], v[52:55]
	v_mfma_f32_16x16x32_f16 v[20:23], v[242:245], v[190:193], v[20:23]
	global_load_lds_dwordx4 v132, s[6:7]
	s_add_u32 m0, s11, 0x7000
	s_waitcnt lgkmcnt(4)
	v_mfma_f32_16x16x32_f16 v[112:115], v[230:233], v[194:197], v[112:115]
	v_mfma_f32_16x16x32_f16 v[80:83], v[234:237], v[194:197], v[80:83]
	v_mfma_f32_16x16x32_f16 v[48:51], v[238:241], v[194:197], v[48:51]
	v_mfma_f32_16x16x32_f16 v[16:19], v[242:245], v[194:197], v[16:19]
	global_load_lds_dwordx4 v133, s[6:7]
	s_add_u32 m0, s11, 0x0
	s_waitcnt lgkmcnt(3)
	v_mfma_f32_16x16x32_f16 v[124:127], v[136:139], v[198:201], v[124:127]
	v_mfma_f32_16x16x32_f16 v[92:95], v[140:143], v[198:201], v[92:95]
	v_mfma_f32_16x16x32_f16 v[60:63], v[144:147], v[198:201], v[60:63]
	v_mfma_f32_16x16x32_f16 v[28:31], v[148:151], v[198:201], v[28:31]
	global_load_lds_dwordx4 v128, s[4:5]
	s_add_u32 m0, s11, 0x1000
	s_waitcnt lgkmcnt(2)
	v_mfma_f32_16x16x32_f16 v[120:123], v[136:139], v[202:205], v[120:123]
	v_mfma_f32_16x16x32_f16 v[88:91], v[140:143], v[202:205], v[88:91]
	v_mfma_f32_16x16x32_f16 v[56:59], v[144:147], v[202:205], v[56:59]
	v_mfma_f32_16x16x32_f16 v[24:27], v[148:151], v[202:205], v[24:27]
	global_load_lds_dwordx4 v129, s[4:5]
	s_add_u32 m0, s11, 0x2000
	s_waitcnt lgkmcnt(1)
	v_mfma_f32_16x16x32_f16 v[116:119], v[136:139], v[222:225], v[116:119]
	v_mfma_f32_16x16x32_f16 v[84:87], v[140:143], v[222:225], v[84:87]
	v_mfma_f32_16x16x32_f16 v[52:55], v[144:147], v[222:225], v[52:55]
	v_mfma_f32_16x16x32_f16 v[20:23], v[148:151], v[222:225], v[20:23]
	global_load_lds_dwordx4 v130, s[4:5]
	s_add_u32 m0, s11, 0x3000
	s_waitcnt lgkmcnt(0)
	v_mfma_f32_16x16x32_f16 v[112:115], v[136:139], v[226:229], v[112:115]
	v_mfma_f32_16x16x32_f16 v[80:83], v[140:143], v[226:229], v[80:83]
	v_mfma_f32_16x16x32_f16 v[48:51], v[144:147], v[226:229], v[48:51]
	v_mfma_f32_16x16x32_f16 v[16:19], v[148:151], v[226:229], v[16:19]
	global_load_lds_dwordx4 v131, s[4:5]
	s_add_u32 s6, s6, 128
	s_addc_u32 s7, s7, 0
	s_add_u32 s4, s4, 128
	s_addc_u32 s5, s5, 0
	s_waitcnt vmcnt(8)
	s_barrier
	ds_read_b128 v[182:185], v176 offset:49152
	ds_read_b128 v[186:189], v176 offset:51200
	ds_read_b128 v[190:193], v176 offset:53248
	ds_read_b128 v[194:197], v176 offset:55296
	ds_read_b128 v[198:201], v178 offset:49152
	ds_read_b128 v[202:205], v178 offset:51200
	ds_read_b128 v[222:225], v178 offset:53248
	ds_read_b128 v[226:229], v178 offset:55296
	s_add_u32 m0, s11, 0x8000
	s_waitcnt lgkmcnt(7)
	v_mfma_f32_16x16x32_f16 v[108:111], v[230:233], v[182:185], v[108:111]
	v_mfma_f32_16x16x32_f16 v[76:79], v[234:237], v[182:185], v[76:79]
	v_mfma_f32_16x16x32_f16 v[44:47], v[238:241], v[182:185], v[44:47]
	v_mfma_f32_16x16x32_f16 v[12:15], v[242:245], v[182:185], v[12:15]
	global_load_lds_dwordx4 v128, s[18:19]
	s_add_u32 m0, s11, 0x9000
	s_waitcnt lgkmcnt(6)
	v_mfma_f32_16x16x32_f16 v[104:107], v[230:233], v[186:189], v[104:107]
	v_mfma_f32_16x16x32_f16 v[72:75], v[234:237], v[186:189], v[72:75]
	v_mfma_f32_16x16x32_f16 v[40:43], v[238:241], v[186:189], v[40:43]
	v_mfma_f32_16x16x32_f16 v[8:11], v[242:245], v[186:189], v[8:11]
	global_load_lds_dwordx4 v129, s[18:19]
	s_add_u32 m0, s11, 0xa000
	s_waitcnt lgkmcnt(5)
	v_mfma_f32_16x16x32_f16 v[100:103], v[230:233], v[190:193], v[100:103]
	v_mfma_f32_16x16x32_f16 v[68:71], v[234:237], v[190:193], v[68:71]
	v_mfma_f32_16x16x32_f16 v[36:39], v[238:241], v[190:193], v[36:39]
	v_mfma_f32_16x16x32_f16 v[4:7], v[242:245], v[190:193], v[4:7]
	global_load_lds_dwordx4 v132, s[18:19]
	s_add_u32 m0, s11, 0xb000
	s_waitcnt lgkmcnt(4)
	v_mfma_f32_16x16x32_f16 v[96:99], v[230:233], v[194:197], v[96:99]
	v_mfma_f32_16x16x32_f16 v[64:67], v[234:237], v[194:197], v[64:67]
	v_mfma_f32_16x16x32_f16 v[32:35], v[238:241], v[194:197], v[32:35]
	v_mfma_f32_16x16x32_f16 v[0:3], v[242:245], v[194:197], v[0:3]
	global_load_lds_dwordx4 v133, s[18:19]
	s_waitcnt lgkmcnt(3)
	v_mfma_f32_16x16x32_f16 v[108:111], v[136:139], v[198:201], v[108:111]
	v_mfma_f32_16x16x32_f16 v[76:79], v[140:143], v[198:201], v[76:79]
	v_mfma_f32_16x16x32_f16 v[44:47], v[144:147], v[198:201], v[44:47]
	v_mfma_f32_16x16x32_f16 v[12:15], v[148:151], v[198:201], v[12:15]
	s_waitcnt lgkmcnt(2)
	v_mfma_f32_16x16x32_f16 v[104:107], v[136:139], v[202:205], v[104:107]
	v_mfma_f32_16x16x32_f16 v[72:75], v[140:143], v[202:205], v[72:75]
	v_mfma_f32_16x16x32_f16 v[40:43], v[144:147], v[202:205], v[40:43]
	v_mfma_f32_16x16x32_f16 v[8:11], v[148:151], v[202:205], v[8:11]
	s_waitcnt lgkmcnt(1)
	v_mfma_f32_16x16x32_f16 v[100:103], v[136:139], v[222:225], v[100:103]
	v_mfma_f32_16x16x32_f16 v[68:71], v[140:143], v[222:225], v[68:71]
	v_mfma_f32_16x16x32_f16 v[36:39], v[144:147], v[222:225], v[36:39]
	v_mfma_f32_16x16x32_f16 v[4:7], v[148:151], v[222:225], v[4:7]
	s_waitcnt lgkmcnt(0)
	v_mfma_f32_16x16x32_f16 v[96:99], v[136:139], v[226:229], v[96:99]
	v_mfma_f32_16x16x32_f16 v[64:67], v[140:143], v[226:229], v[64:67]
	v_mfma_f32_16x16x32_f16 v[32:35], v[144:147], v[226:229], v[32:35]
	v_mfma_f32_16x16x32_f16 v[0:3], v[148:151], v[226:229], v[0:3]
	s_add_u32 s18, s18, 128
	s_addc_u32 s19, s19, 0
	s_add_i32 s10, s10, 1
	s_cmp_lt_u32 s10, 10
	s_cbranch_scc1 .Lgin_loop
	s_waitcnt vmcnt(4)
	s_barrier
	ds_read_b128 v[230:233], v175 offset:0
	ds_read_b128 v[234:237], v175 offset:2048
	ds_read_b128 v[238:241], v175 offset:4096
	ds_read_b128 v[242:245], v175 offset:6144
	ds_read_b128 v[136:139], v177 offset:0
	ds_read_b128 v[140:143], v177 offset:2048
	ds_read_b128 v[144:147], v177 offset:4096
	ds_read_b128 v[148:151], v177 offset:6144
	ds_read_b128 v[182:185], v176 offset:16384
	ds_read_b128 v[186:189], v176 offset:18432
	ds_read_b128 v[190:193], v176 offset:20480
	ds_read_b128 v[194:197], v176 offset:22528
	s_add_u32 m0, s11, 0xc000
	s_waitcnt lgkmcnt(3)
	v_mfma_f32_16x16x32_f16 v[124:127], v[230:233], v[182:185], v[124:127]
	v_mfma_f32_16x16x32_f16 v[92:95], v[234:237], v[182:185], v[92:95]
	v_mfma_f32_16x16x32_f16 v[60:63], v[238:241], v[182:185], v[60:63]
	v_mfma_f32_16x16x32_f16 v[28:31], v[242:245], v[182:185], v[28:31]
	global_load_lds_dwordx4 v128, s[6:7]
	s_barrier
	ds_read_b128 v[198:201], v178 offset:16384
	ds_read_b128 v[202:205], v178 offset:18432
	ds_read_b128 v[222:225], v178 offset:20480
	ds_read_b128 v[226:229], v178 offset:22528
	s_add_u32 m0, s11, 0xd000
	s_waitcnt lgkmcnt(6)
	v_mfma_f32_16x16x32_f16 v[120:123], v[230:233], v[186:189], v[120:123]
	v_mfma_f32_16x16x32_f16 v[88:91], v[234:237], v[186:189], v[88:91]
	v_mfma_f32_16x16x32_f16 v[56:59], v[238:241], v[186:189], v[56:59]
	v_mfma_f32_16x16x32_f16 v[24:27], v[242:245], v[186:189], v[24:27]
	global_load_lds_dwordx4 v129, s[6:7]
	s_add_u32 m0, s11, 0xe000
	s_waitcnt lgkmcnt(5)
	v_mfma_f32_16x16x32_f16 v[116:119], v[230:233], v[190:193], v[116:119]
	v_mfma_f32_16x16x32_f16 v[84:87], v[234:237], v[190:193], v[84:87]
	v_mfma_f32_16x16x32_f16 v[52:55], v[238:241], v[190:193], v[52:55]
	v_mfma_f32_16x16x32_f16 v[20:23], v[242:245], v[190:193], v[20:23]
	global_load_lds_dwordx4 v132, s[6:7]
	s_add_u32 m0, s11, 0xf000
	s_waitcnt lgkmcnt(4)
	v_mfma_f32_16x16x32_f16 v[112:115], v[230:233], v[194:197], v[112:115]
	v_mfma_f32_16x16x32_f16 v[80:83], v[234:237], v[194:197], v[80:83]
	v_mfma_f32_16x16x32_f16 v[48:51], v[238:241], v[194:197], v[48:51]
	v_mfma_f32_16x16x32_f16 v[16:19], v[242:245], v[194:197], v[16:19]
	global_load_lds_dwordx4 v133, s[6:7]
	s_add_u32 m0, s11, 0x0
	s_waitcnt lgkmcnt(3)
	v_mfma_f32_16x16x32_f16 v[124:127], v[136:139], v[198:201], v[124:127]
	v_mfma_f32_16x16x32_f16 v[92:95], v[140:143], v[198:201], v[92:95]
	v_mfma_f32_16x16x32_f16 v[60:63], v[144:147], v[198:201], v[60:63]
	v_mfma_f32_16x16x32_f16 v[28:31], v[148:151], v[198:201], v[28:31]
	global_load_lds_dwordx4 v128, s[4:5]
	s_add_u32 m0, s11, 0x1000
	s_waitcnt lgkmcnt(2)
	v_mfma_f32_16x16x32_f16 v[120:123], v[136:139], v[202:205], v[120:123]
	v_mfma_f32_16x16x32_f16 v[88:91], v[140:143], v[202:205], v[88:91]
	v_mfma_f32_16x16x32_f16 v[56:59], v[144:147], v[202:205], v[56:59]
	v_mfma_f32_16x16x32_f16 v[24:27], v[148:151], v[202:205], v[24:27]
	global_load_lds_dwordx4 v129, s[4:5]
	s_add_u32 m0, s11, 0x2000
	s_waitcnt lgkmcnt(1)
	v_mfma_f32_16x16x32_f16 v[116:119], v[136:139], v[222:225], v[116:119]
	v_mfma_f32_16x16x32_f16 v[84:87], v[140:143], v[222:225], v[84:87]
	v_mfma_f32_16x16x32_f16 v[52:55], v[144:147], v[222:225], v[52:55]
	v_mfma_f32_16x16x32_f16 v[20:23], v[148:151], v[222:225], v[20:23]
	global_load_lds_dwordx4 v130, s[4:5]
	s_add_u32 m0, s11, 0x3000
	s_waitcnt lgkmcnt(0)
	v_mfma_f32_16x16x32_f16 v[112:115], v[136:139], v[226:229], v[112:115]
	v_mfma_f32_16x16x32_f16 v[80:83], v[140:143], v[226:229], v[80:83]
	v_mfma_f32_16x16x32_f16 v[48:51], v[144:147], v[226:229], v[48:51]
	v_mfma_f32_16x16x32_f16 v[16:19], v[148:151], v[226:229], v[16:19]
	global_load_lds_dwordx4 v131, s[4:5]
	s_add_u32 s6, s6, 128
	s_addc_u32 s7, s7, 0
	s_add_u32 s4, s4, 128
	s_addc_u32 s5, s5, 0
	s_waitcnt vmcnt(8)
	s_barrier
	ds_read_b128 v[182:185], v176 offset:32768
	ds_read_b128 v[186:189], v176 offset:34816
	ds_read_b128 v[190:193], v176 offset:36864
	ds_read_b128 v[194:197], v176 offset:38912
	ds_read_b128 v[198:201], v178 offset:32768
	ds_read_b128 v[202:205], v178 offset:34816
	ds_read_b128 v[222:225], v178 offset:36864
	ds_read_b128 v[226:229], v178 offset:38912
	s_add_u32 m0, s11, 0x4000
	s_waitcnt lgkmcnt(7)
	v_mfma_f32_16x16x32_f16 v[108:111], v[230:233], v[182:185], v[108:111]
	v_mfma_f32_16x16x32_f16 v[76:79], v[234:237], v[182:185], v[76:79]
	v_mfma_f32_16x16x32_f16 v[44:47], v[238:241], v[182:185], v[44:47]
	v_mfma_f32_16x16x32_f16 v[12:15], v[242:245], v[182:185], v[12:15]
	global_load_lds_dwordx4 v128, s[18:19]
	s_add_u32 m0, s11, 0x5000
	s_waitcnt lgkmcnt(6)
	v_mfma_f32_16x16x32_f16 v[104:107], v[230:233], v[186:189], v[104:107]
	v_mfma_f32_16x16x32_f16 v[72:75], v[234:237], v[186:189], v[72:75]
	v_mfma_f32_16x16x32_f16 v[40:43], v[238:241], v[186:189], v[40:43]
	v_mfma_f32_16x16x32_f16 v[8:11], v[242:245], v[186:189], v[8:11]
	global_load_lds_dwordx4 v129, s[18:19]
	s_add_u32 m0, s11, 0x6000
	s_waitcnt lgkmcnt(5)
	v_mfma_f32_16x16x32_f16 v[100:103], v[230:233], v[190:193], v[100:103]
	v_mfma_f32_16x16x32_f16 v[68:71], v[234:237], v[190:193], v[68:71]
	v_mfma_f32_16x16x32_f16 v[36:39], v[238:241], v[190:193], v[36:39]
	v_mfma_f32_16x16x32_f16 v[4:7], v[242:245], v[190:193], v[4:7]
	global_load_lds_dwordx4 v132, s[18:19]
	s_add_u32 m0, s11, 0x7000
	s_waitcnt lgkmcnt(4)
	v_mfma_f32_16x16x32_f16 v[96:99], v[230:233], v[194:197], v[96:99]
	v_mfma_f32_16x16x32_f16 v[64:67], v[234:237], v[194:197], v[64:67]
	v_mfma_f32_16x16x32_f16 v[32:35], v[238:241], v[194:197], v[32:35]
	v_mfma_f32_16x16x32_f16 v[0:3], v[242:245], v[194:197], v[0:3]
	global_load_lds_dwordx4 v133, s[18:19]
	s_waitcnt lgkmcnt(3)
	v_mfma_f32_16x16x32_f16 v[108:111], v[136:139], v[198:201], v[108:111]
	v_mfma_f32_16x16x32_f16 v[76:79], v[140:143], v[198:201], v[76:79]
	v_mfma_f32_16x16x32_f16 v[44:47], v[144:147], v[198:201], v[44:47]
	v_mfma_f32_16x16x32_f16 v[12:15], v[148:151], v[198:201], v[12:15]
	s_waitcnt lgkmcnt(2)
	v_mfma_f32_16x16x32_f16 v[104:107], v[136:139], v[202:205], v[104:107]
	v_mfma_f32_16x16x32_f16 v[72:75], v[140:143], v[202:205], v[72:75]
	v_mfma_f32_16x16x32_f16 v[40:43], v[144:147], v[202:205], v[40:43]
	v_mfma_f32_16x16x32_f16 v[8:11], v[148:151], v[202:205], v[8:11]
	s_waitcnt lgkmcnt(1)
	v_mfma_f32_16x16x32_f16 v[100:103], v[136:139], v[222:225], v[100:103]
	v_mfma_f32_16x16x32_f16 v[68:71], v[140:143], v[222:225], v[68:71]
	v_mfma_f32_16x16x32_f16 v[36:39], v[144:147], v[222:225], v[36:39]
	v_mfma_f32_16x16x32_f16 v[4:7], v[148:151], v[222:225], v[4:7]
	s_waitcnt lgkmcnt(0)
	v_mfma_f32_16x16x32_f16 v[96:99], v[136:139], v[226:229], v[96:99]
	v_mfma_f32_16x16x32_f16 v[64:67], v[140:143], v[226:229], v[64:67]
	v_mfma_f32_16x16x32_f16 v[32:35], v[144:147], v[226:229], v[32:35]
	v_mfma_f32_16x16x32_f16 v[0:3], v[148:151], v[226:229], v[0:3]
	s_add_u32 s18, s18, 128
	s_addc_u32 s19, s19, 0
	s_waitcnt vmcnt(4)
	s_barrier
	ds_read_b128 v[230:233], v175 offset:0
	ds_read_b128 v[234:237], v175 offset:2048
	ds_read_b128 v[238:241], v175 offset:4096
	ds_read_b128 v[242:245], v175 offset:6144
	ds_read_b128 v[136:139], v177 offset:0
	ds_read_b128 v[140:143], v177 offset:2048
	ds_read_b128 v[144:147], v177 offset:4096
	ds_read_b128 v[148:151], v177 offset:6144
	ds_read_b128 v[182:185], v176 offset:49152
	ds_read_b128 v[186:189], v176 offset:51200
	ds_read_b128 v[190:193], v176 offset:53248
	ds_read_b128 v[194:197], v176 offset:55296
	s_waitcnt lgkmcnt(3)
	v_mfma_f32_16x16x32_f16 v[124:127], v[230:233], v[182:185], v[124:127]
	v_mfma_f32_16x16x32_f16 v[92:95], v[234:237], v[182:185], v[92:95]
	v_mfma_f32_16x16x32_f16 v[60:63], v[238:241], v[182:185], v[60:63]
	v_mfma_f32_16x16x32_f16 v[28:31], v[242:245], v[182:185], v[28:31]
	s_barrier
	ds_read_b128 v[198:201], v178 offset:49152
	ds_read_b128 v[202:205], v178 offset:51200
	ds_read_b128 v[222:225], v178 offset:53248
	ds_read_b128 v[226:229], v178 offset:55296
	s_waitcnt lgkmcnt(6)
	v_mfma_f32_16x16x32_f16 v[120:123], v[230:233], v[186:189], v[120:123]
	v_mfma_f32_16x16x32_f16 v[88:91], v[234:237], v[186:189], v[88:91]
	v_mfma_f32_16x16x32_f16 v[56:59], v[238:241], v[186:189], v[56:59]
	v_mfma_f32_16x16x32_f16 v[24:27], v[242:245], v[186:189], v[24:27]
	s_waitcnt lgkmcnt(5)
	v_mfma_f32_16x16x32_f16 v[116:119], v[230:233], v[190:193], v[116:119]
	v_mfma_f32_16x16x32_f16 v[84:87], v[234:237], v[190:193], v[84:87]
	v_mfma_f32_16x16x32_f16 v[52:55], v[238:241], v[190:193], v[52:55]
	v_mfma_f32_16x16x32_f16 v[20:23], v[242:245], v[190:193], v[20:23]
	s_waitcnt lgkmcnt(4)
	v_mfma_f32_16x16x32_f16 v[112:115], v[230:233], v[194:197], v[112:115]
	v_mfma_f32_16x16x32_f16 v[80:83], v[234:237], v[194:197], v[80:83]
	v_mfma_f32_16x16x32_f16 v[48:51], v[238:241], v[194:197], v[48:51]
	v_mfma_f32_16x16x32_f16 v[16:19], v[242:245], v[194:197], v[16:19]
	s_waitcnt lgkmcnt(3)
	v_mfma_f32_16x16x32_f16 v[124:127], v[136:139], v[198:201], v[124:127]
	v_mfma_f32_16x16x32_f16 v[92:95], v[140:143], v[198:201], v[92:95]
	v_mfma_f32_16x16x32_f16 v[60:63], v[144:147], v[198:201], v[60:63]
	v_mfma_f32_16x16x32_f16 v[28:31], v[148:151], v[198:201], v[28:31]
	s_waitcnt lgkmcnt(2)
	v_mfma_f32_16x16x32_f16 v[120:123], v[136:139], v[202:205], v[120:123]
	v_mfma_f32_16x16x32_f16 v[88:91], v[140:143], v[202:205], v[88:91]
	v_mfma_f32_16x16x32_f16 v[56:59], v[144:147], v[202:205], v[56:59]
	v_mfma_f32_16x16x32_f16 v[24:27], v[148:151], v[202:205], v[24:27]
	s_waitcnt lgkmcnt(1)
	v_mfma_f32_16x16x32_f16 v[116:119], v[136:139], v[222:225], v[116:119]
	v_mfma_f32_16x16x32_f16 v[84:87], v[140:143], v[222:225], v[84:87]
	v_mfma_f32_16x16x32_f16 v[52:55], v[144:147], v[222:225], v[52:55]
	v_mfma_f32_16x16x32_f16 v[20:23], v[148:151], v[222:225], v[20:23]
	s_waitcnt lgkmcnt(0)
	v_mfma_f32_16x16x32_f16 v[112:115], v[136:139], v[226:229], v[112:115]
	v_mfma_f32_16x16x32_f16 v[80:83], v[140:143], v[226:229], v[80:83]
	v_mfma_f32_16x16x32_f16 v[48:51], v[144:147], v[226:229], v[48:51]
	v_mfma_f32_16x16x32_f16 v[16:19], v[148:151], v[226:229], v[16:19]
	s_waitcnt vmcnt(0)
	s_barrier
	ds_read_b128 v[182:185], v176 offset:16384
	ds_read_b128 v[186:189], v176 offset:18432
	ds_read_b128 v[190:193], v176 offset:20480
	ds_read_b128 v[194:197], v176 offset:22528
	ds_read_b128 v[198:201], v178 offset:16384
	ds_read_b128 v[202:205], v178 offset:18432
	ds_read_b128 v[222:225], v178 offset:20480
	ds_read_b128 v[226:229], v178 offset:22528
	s_waitcnt lgkmcnt(7)
	v_mfma_f32_16x16x32_f16 v[108:111], v[230:233], v[182:185], v[108:111]
	v_mfma_f32_16x16x32_f16 v[76:79], v[234:237], v[182:185], v[76:79]
	v_mfma_f32_16x16x32_f16 v[44:47], v[238:241], v[182:185], v[44:47]
	v_mfma_f32_16x16x32_f16 v[12:15], v[242:245], v[182:185], v[12:15]
	s_waitcnt lgkmcnt(6)
	v_mfma_f32_16x16x32_f16 v[104:107], v[230:233], v[186:189], v[104:107]
	v_mfma_f32_16x16x32_f16 v[72:75], v[234:237], v[186:189], v[72:75]
	v_mfma_f32_16x16x32_f16 v[40:43], v[238:241], v[186:189], v[40:43]
	v_mfma_f32_16x16x32_f16 v[8:11], v[242:245], v[186:189], v[8:11]
	s_waitcnt lgkmcnt(5)
	v_mfma_f32_16x16x32_f16 v[100:103], v[230:233], v[190:193], v[100:103]
	v_mfma_f32_16x16x32_f16 v[68:71], v[234:237], v[190:193], v[68:71]
	v_mfma_f32_16x16x32_f16 v[36:39], v[238:241], v[190:193], v[36:39]
	v_mfma_f32_16x16x32_f16 v[4:7], v[242:245], v[190:193], v[4:7]
	s_waitcnt lgkmcnt(4)
	v_mfma_f32_16x16x32_f16 v[96:99], v[230:233], v[194:197], v[96:99]
	v_mfma_f32_16x16x32_f16 v[64:67], v[234:237], v[194:197], v[64:67]
	v_mfma_f32_16x16x32_f16 v[32:35], v[238:241], v[194:197], v[32:35]
	v_mfma_f32_16x16x32_f16 v[0:3], v[242:245], v[194:197], v[0:3]
	s_waitcnt lgkmcnt(3)
	v_mfma_f32_16x16x32_f16 v[108:111], v[136:139], v[198:201], v[108:111]
	v_mfma_f32_16x16x32_f16 v[76:79], v[140:143], v[198:201], v[76:79]
	v_mfma_f32_16x16x32_f16 v[44:47], v[144:147], v[198:201], v[44:47]
	v_mfma_f32_16x16x32_f16 v[12:15], v[148:151], v[198:201], v[12:15]
	s_waitcnt lgkmcnt(2)
	v_mfma_f32_16x16x32_f16 v[104:107], v[136:139], v[202:205], v[104:107]
	v_mfma_f32_16x16x32_f16 v[72:75], v[140:143], v[202:205], v[72:75]
	v_mfma_f32_16x16x32_f16 v[40:43], v[144:147], v[202:205], v[40:43]
	v_mfma_f32_16x16x32_f16 v[8:11], v[148:151], v[202:205], v[8:11]
	s_waitcnt lgkmcnt(1)
	v_mfma_f32_16x16x32_f16 v[100:103], v[136:139], v[222:225], v[100:103]
	v_mfma_f32_16x16x32_f16 v[68:71], v[140:143], v[222:225], v[68:71]
	v_mfma_f32_16x16x32_f16 v[36:39], v[144:147], v[222:225], v[36:39]
	v_mfma_f32_16x16x32_f16 v[4:7], v[148:151], v[222:225], v[4:7]
	s_waitcnt lgkmcnt(0)
	v_mfma_f32_16x16x32_f16 v[96:99], v[136:139], v[226:229], v[96:99]
	v_mfma_f32_16x16x32_f16 v[64:67], v[140:143], v[226:229], v[64:67]
	v_mfma_f32_16x16x32_f16 v[32:35], v[144:147], v[226:229], v[32:35]
	v_mfma_f32_16x16x32_f16 v[0:3], v[148:151], v[226:229], v[0:3]
	s_nop 7
	s_cmpk_lt_u32 s9, 0x620
	s_cbranch_scc0 .Lgin_cls_lat
	s_cmp_lt_u32 s16, 4
	s_cbranch_scc1 .Lgin_plain
	s_sub_u32 s4, s16, 8
	s_cmp_lt_u32 s4, 28
	s_cbranch_scc1 .Lgin_plain
	s_sub_u32 s4, s16, 45
	s_cmp_lt_u32 s4, 3
	s_cbranch_scc1 .Lgin_plain
	s_sub_u32 s4, s16, 4
	s_cmp_lt_u32 s4, 2
	s_cbranch_scc1 .Lgin_kvar
	s_sub_u32 s4, s16, 37
	s_cmp_lt_u32 s4, 3
	s_cbranch_scc1 .Lgin_kvar
	s_branch .Lgin_notplain
.Lgin_cls_lat:
	s_sub_u32 s4, s16, 8
	s_cmp_lt_u32 s4, 32
	s_cbranch_scc1 .Lgin_plain
	s_sub_u32 s4, s16, 45
	s_cmp_lt_u32 s4, 3
	s_cbranch_scc0 .Lgin_notplain
.Lgin_plain:
	s_mul_i32 s6, s0, 0x3020
	s_lshl_b32 s7, s16, 8
	v_readlane_b32 s4, v254, 4
	v_readlane_b32 s5, v254, 5
	v_add_u32_e32 v128, v174, v166
	v_add_u32_e32 v129, v173, v179
	v_mul_u32_u24_e32 v128, 0x3020, v128
	s_add_u32 s6, s6, s7
	v_lshl_add_u32 v128, v129, 1, v128
	s_add_u32 s4, s4, s6
	s_addc_u32 s5, s5, 0
	v_cvt_pk_f16_f32 v124, v124, v125
	v_cvt_pk_f16_f32 v125, v126, v127
	global_store_dwordx2 v128, v[124:125], s[4:5]
	v_cvt_pk_f16_f32 v92, v92, v93
	v_cvt_pk_f16_f32 v93, v94, v95
	global_store_dwordx2 v128, v[92:93], s[4:5] offset:32
	v_cvt_pk_f16_f32 v60, v60, v61
	v_cvt_pk_f16_f32 v61, v62, v63
	global_store_dwordx2 v128, v[60:61], s[4:5] offset:64
	v_cvt_pk_f16_f32 v28, v28, v29
	v_cvt_pk_f16_f32 v29, v30, v31
	global_store_dwordx2 v128, v[28:29], s[4:5] offset:96
	s_add_u32 s4, s4, 0x30200
	s_addc_u32 s5, s5, 0
	v_cvt_pk_f16_f32 v120, v120, v121
	v_cvt_pk_f16_f32 v121, v122, v123
	global_store_dwordx2 v128, v[120:121], s[4:5]
	v_cvt_pk_f16_f32 v88, v88, v89
	v_cvt_pk_f16_f32 v89, v90, v91
	global_store_dwordx2 v128, v[88:89], s[4:5] offset:32
	v_cvt_pk_f16_f32 v56, v56, v57
	v_cvt_pk_f16_f32 v57, v58, v59
	global_store_dwordx2 v128, v[56:57], s[4:5] offset:64
	v_cvt_pk_f16_f32 v24, v24, v25
	v_cvt_pk_f16_f32 v25, v26, v27
	global_store_dwordx2 v128, v[24:25], s[4:5] offset:96
	s_add_u32 s4, s4, 0x30200
	s_addc_u32 s5, s5, 0
	v_cvt_pk_f16_f32 v116, v116, v117
	v_cvt_pk_f16_f32 v117, v118, v119
	global_store_dwordx2 v128, v[116:117], s[4:5]
	v_cvt_pk_f16_f32 v84, v84, v85
	v_cvt_pk_f16_f32 v85, v86, v87
	global_store_dwordx2 v128, v[84:85], s[4:5] offset:32
	v_cvt_pk_f16_f32 v52, v52, v53
	v_cvt_pk_f16_f32 v53, v54, v55
	global_store_dwordx2 v128, v[52:53], s[4:5] offset:64
	v_cvt_pk_f16_f32 v20, v20, v21
	v_cvt_pk_f16_f32 v21, v22, v23
	global_store_dwordx2 v128, v[20:21], s[4:5] offset:96
	s_add_u32 s4, s4, 0x30200
	s_addc_u32 s5, s5, 0
	v_cvt_pk_f16_f32 v112, v112, v113
	v_cvt_pk_f16_f32 v113, v114, v115
	global_store_dwordx2 v128, v[112:113], s[4:5]
	v_cvt_pk_f16_f32 v80, v80, v81
	v_cvt_pk_f16_f32 v81, v82, v83
	global_store_dwordx2 v128, v[80:81], s[4:5] offset:32
	v_cvt_pk_f16_f32 v48, v48, v49
	v_cvt_pk_f16_f32 v49, v50, v51
	global_store_dwordx2 v128, v[48:49], s[4:5] offset:64
	v_cvt_pk_f16_f32 v16, v16, v17
	v_cvt_pk_f16_f32 v17, v18, v19
	global_store_dwordx2 v128, v[16:17], s[4:5] offset:96
	s_add_u32 s4, s4, 0x30200
	s_addc_u32 s5, s5, 0
	v_cvt_pk_f16_f32 v108, v108, v109
	v_cvt_pk_f16_f32 v109, v110, v111
	global_store_dwordx2 v128, v[108:109], s[4:5]
	v_cvt_pk_f16_f32 v76, v76, v77
	v_cvt_pk_f16_f32 v77, v78, v79
	global_store_dwordx2 v128, v[76:77], s[4:5] offset:32
	v_cvt_pk_f16_f32 v44, v44, v45
	v_cvt_pk_f16_f32 v45, v46, v47
	global_store_dwordx2 v128, v[44:45], s[4:5] offset:64
	v_cvt_pk_f16_f32 v12, v12, v13
	v_cvt_pk_f16_f32 v13, v14, v15
	global_store_dwordx2 v128, v[12:13], s[4:5] offset:96
	s_add_u32 s4, s4, 0x30200
	s_addc_u32 s5, s5, 0
	v_cvt_pk_f16_f32 v104, v104, v105
	v_cvt_pk_f16_f32 v105, v106, v107
	global_store_dwordx2 v128, v[104:105], s[4:5]
	v_cvt_pk_f16_f32 v72, v72, v73
	v_cvt_pk_f16_f32 v73, v74, v75
	global_store_dwordx2 v128, v[72:73], s[4:5] offset:32
	v_cvt_pk_f16_f32 v40, v40, v41
	v_cvt_pk_f16_f32 v41, v42, v43
	global_store_dwordx2 v128, v[40:41], s[4:5] offset:64
	v_cvt_pk_f16_f32 v8, v8, v9
	v_cvt_pk_f16_f32 v9, v10, v11
	global_store_dwordx2 v128, v[8:9], s[4:5] offset:96
	s_add_u32 s4, s4, 0x30200
	s_addc_u32 s5, s5, 0
	v_cvt_pk_f16_f32 v100, v100, v101
	v_cvt_pk_f16_f32 v101, v102, v103
	global_store_dwordx2 v128, v[100:101], s[4:5]
	v_cvt_pk_f16_f32 v68, v68, v69
	v_cvt_pk_f16_f32 v69, v70, v71
	global_store_dwordx2 v128, v[68:69], s[4:5] offset:32
	v_cvt_pk_f16_f32 v36, v36, v37
	v_cvt_pk_f16_f32 v37, v38, v39
	global_store_dwordx2 v128, v[36:37], s[4:5] offset:64
	v_cvt_pk_f16_f32 v4, v4, v5
	v_cvt_pk_f16_f32 v5, v6, v7
	global_store_dwordx2 v128, v[4:5], s[4:5] offset:96
	s_add_u32 s4, s4, 0x30200
	s_addc_u32 s5, s5, 0
	v_cvt_pk_f16_f32 v96, v96, v97
	v_cvt_pk_f16_f32 v97, v98, v99
	global_store_dwordx2 v128, v[96:97], s[4:5]
	v_cvt_pk_f16_f32 v64, v64, v65
	v_cvt_pk_f16_f32 v65, v66, v67
	global_store_dwordx2 v128, v[64:65], s[4:5] offset:32
	v_cvt_pk_f16_f32 v32, v32, v33
	v_cvt_pk_f16_f32 v33, v34, v35
	global_store_dwordx2 v128, v[32:33], s[4:5] offset:64
	v_cvt_pk_f16_f32 v0, v0, v1
	v_cvt_pk_f16_f32 v1, v2, v3
	global_store_dwordx2 v128, v[0:1], s[4:5] offset:96
	s_mov_b64 s[50:51], exec
	s_branch .LBB0_315
.Lgin_kvar:
	s_lshr_b32 s6, s0, 8
	s_lshl_b32 s6, s6, 1
	v_readlane_b32 s7, v255, 43
	s_cmp_lt_u32 s16, 6
	s_cselect_b32 s8, 8, 9
	s_mov_b32 s10, 33549808
	s_cselect_b32 s10, 25165312, s10
	s_add_u32 s6, s6, s7
	s_lshl_b32 s6, s6, 8
	s_lshl_b32 s7, s16, 7
	s_add_u32 s10, s10, s7
	s_lshl_b32 s6, s6, s8
	s_add_u32 s6, s6, s10
	s_lshl_b32 s6, s6, 2
	s_add_u32 s10, s94, s6
	s_addc_u32 s11, s95, 0
	s_lshl_b32 s18, 64, s8
	v_add_u32_e32 v130, v174, v166
	v_lshlrev_b32_e32 v130, s8, v130
	v_add3_u32 v130, v130, v173, v179
	v_lshlrev_b32_e32 v130, 2, v130
	s_mul_i32 s6, s0, 0x3020
	s_lshl_b32 s7, s16, 8
	v_readlane_b32 s4, v254, 4
	v_readlane_b32 s5, v254, 5
	v_add_u32_e32 v128, v174, v166
	v_add_u32_e32 v129, v173, v179
	v_mul_u32_u24_e32 v128, 0x3020, v128
	s_add_u32 s6, s6, s7
	v_lshl_add_u32 v128, v129, 1, v128
	s_add_u32 s4, s4, s6
	s_addc_u32 s5, s5, 0
	global_store_dwordx4 v130, v[124:127], s[10:11] nt
	s_nop 1
	v_cvt_pk_f16_f32 v124, v124, v125
	v_cvt_pk_f16_f32 v125, v126, v127
	global_store_dwordx2 v128, v[124:125], s[4:5]
	global_store_dwordx4 v130, v[92:95], s[10:11] offset:64 nt
	s_nop 1
	v_cvt_pk_f16_f32 v92, v92, v93
	v_cvt_pk_f16_f32 v93, v94, v95
	global_store_dwordx2 v128, v[92:93], s[4:5] offset:32
	global_store_dwordx4 v130, v[60:63], s[10:11] offset:128 nt
	s_nop 1
	v_cvt_pk_f16_f32 v60, v60, v61
	v_cvt_pk_f16_f32 v61, v62, v63
	global_store_dwordx2 v128, v[60:61], s[4:5] offset:64
	global_store_dwordx4 v130, v[28:31], s[10:11] offset:192 nt
	s_nop 1
	v_cvt_pk_f16_f32 v28, v28, v29
	v_cvt_pk_f16_f32 v29, v30, v31
	global_store_dwordx2 v128, v[28:29], s[4:5] offset:96
	s_add_u32 s4, s4, 0x30200
	s_addc_u32 s5, s5, 0
	s_add_u32 s10, s10, s18
	s_addc_u32 s11, s11, 0
	global_store_dwordx4 v130, v[120:123], s[10:11] nt
	s_nop 1
	v_cvt_pk_f16_f32 v120, v120, v121
	v_cvt_pk_f16_f32 v121, v122, v123
	global_store_dwordx2 v128, v[120:121], s[4:5]
	global_store_dwordx4 v130, v[88:91], s[10:11] offset:64 nt
	s_nop 1
	v_cvt_pk_f16_f32 v88, v88, v89
	v_cvt_pk_f16_f32 v89, v90, v91
	global_store_dwordx2 v128, v[88:89], s[4:5] offset:32
	global_store_dwordx4 v130, v[56:59], s[10:11] offset:128 nt
	s_nop 1
	v_cvt_pk_f16_f32 v56, v56, v57
	v_cvt_pk_f16_f32 v57, v58, v59
	global_store_dwordx2 v128, v[56:57], s[4:5] offset:64
	global_store_dwordx4 v130, v[24:27], s[10:11] offset:192 nt
	s_nop 1
	v_cvt_pk_f16_f32 v24, v24, v25
	v_cvt_pk_f16_f32 v25, v26, v27
	global_store_dwordx2 v128, v[24:25], s[4:5] offset:96
	s_add_u32 s4, s4, 0x30200
	s_addc_u32 s5, s5, 0
	s_add_u32 s10, s10, s18
	s_addc_u32 s11, s11, 0
	global_store_dwordx4 v130, v[116:119], s[10:11] nt
	s_nop 1
	v_cvt_pk_f16_f32 v116, v116, v117
	v_cvt_pk_f16_f32 v117, v118, v119
	global_store_dwordx2 v128, v[116:117], s[4:5]
	global_store_dwordx4 v130, v[84:87], s[10:11] offset:64 nt
	s_nop 1
	v_cvt_pk_f16_f32 v84, v84, v85
	v_cvt_pk_f16_f32 v85, v86, v87
	global_store_dwordx2 v128, v[84:85], s[4:5] offset:32
	global_store_dwordx4 v130, v[52:55], s[10:11] offset:128 nt
	s_nop 1
	v_cvt_pk_f16_f32 v52, v52, v53
	v_cvt_pk_f16_f32 v53, v54, v55
	global_store_dwordx2 v128, v[52:53], s[4:5] offset:64
	global_store_dwordx4 v130, v[20:23], s[10:11] offset:192 nt
	s_nop 1
	v_cvt_pk_f16_f32 v20, v20, v21
	v_cvt_pk_f16_f32 v21, v22, v23
	global_store_dwordx2 v128, v[20:21], s[4:5] offset:96
	s_add_u32 s4, s4, 0x30200
	s_addc_u32 s5, s5, 0
	s_add_u32 s10, s10, s18
	s_addc_u32 s11, s11, 0
	global_store_dwordx4 v130, v[112:115], s[10:11] nt
	s_nop 1
	v_cvt_pk_f16_f32 v112, v112, v113
	v_cvt_pk_f16_f32 v113, v114, v115
	global_store_dwordx2 v128, v[112:113], s[4:5]
	global_store_dwordx4 v130, v[80:83], s[10:11] offset:64 nt
	s_nop 1
	v_cvt_pk_f16_f32 v80, v80, v81
	v_cvt_pk_f16_f32 v81, v82, v83
	global_store_dwordx2 v128, v[80:81], s[4:5] offset:32
	global_store_dwordx4 v130, v[48:51], s[10:11] offset:128 nt
	s_nop 1
	v_cvt_pk_f16_f32 v48, v48, v49
	v_cvt_pk_f16_f32 v49, v50, v51
	global_store_dwordx2 v128, v[48:49], s[4:5] offset:64
	global_store_dwordx4 v130, v[16:19], s[10:11] offset:192 nt
	s_nop 1
	v_cvt_pk_f16_f32 v16, v16, v17
	v_cvt_pk_f16_f32 v17, v18, v19
	global_store_dwordx2 v128, v[16:17], s[4:5] offset:96
	s_add_u32 s4, s4, 0x30200
	s_addc_u32 s5, s5, 0
	s_add_u32 s10, s10, s18
	s_addc_u32 s11, s11, 0
	global_store_dwordx4 v130, v[108:111], s[10:11] nt
	s_nop 1
	v_cvt_pk_f16_f32 v108, v108, v109
	v_cvt_pk_f16_f32 v109, v110, v111
	global_store_dwordx2 v128, v[108:109], s[4:5]
	global_store_dwordx4 v130, v[76:79], s[10:11] offset:64 nt
	s_nop 1
	v_cvt_pk_f16_f32 v76, v76, v77
	v_cvt_pk_f16_f32 v77, v78, v79
	global_store_dwordx2 v128, v[76:77], s[4:5] offset:32
	global_store_dwordx4 v130, v[44:47], s[10:11] offset:128 nt
	s_nop 1
	v_cvt_pk_f16_f32 v44, v44, v45
	v_cvt_pk_f16_f32 v45, v46, v47
	global_store_dwordx2 v128, v[44:45], s[4:5] offset:64
	global_store_dwordx4 v130, v[12:15], s[10:11] offset:192 nt
	s_nop 1
	v_cvt_pk_f16_f32 v12, v12, v13
	v_cvt_pk_f16_f32 v13, v14, v15
	global_store_dwordx2 v128, v[12:13], s[4:5] offset:96
	s_add_u32 s4, s4, 0x30200
	s_addc_u32 s5, s5, 0
	s_add_u32 s10, s10, s18
	s_addc_u32 s11, s11, 0
	global_store_dwordx4 v130, v[104:107], s[10:11] nt
	s_nop 1
	v_cvt_pk_f16_f32 v104, v104, v105
	v_cvt_pk_f16_f32 v105, v106, v107
	global_store_dwordx2 v128, v[104:105], s[4:5]
	global_store_dwordx4 v130, v[72:75], s[10:11] offset:64 nt
	s_nop 1
	v_cvt_pk_f16_f32 v72, v72, v73
	v_cvt_pk_f16_f32 v73, v74, v75
	global_store_dwordx2 v128, v[72:73], s[4:5] offset:32
	global_store_dwordx4 v130, v[40:43], s[10:11] offset:128 nt
	s_nop 1
	v_cvt_pk_f16_f32 v40, v40, v41
	v_cvt_pk_f16_f32 v41, v42, v43
	global_store_dwordx2 v128, v[40:41], s[4:5] offset:64
	global_store_dwordx4 v130, v[8:11], s[10:11] offset:192 nt
	s_nop 1
	v_cvt_pk_f16_f32 v8, v8, v9
	v_cvt_pk_f16_f32 v9, v10, v11
	global_store_dwordx2 v128, v[8:9], s[4:5] offset:96
	s_add_u32 s4, s4, 0x30200
	s_addc_u32 s5, s5, 0
	s_add_u32 s10, s10, s18
	s_addc_u32 s11, s11, 0
	global_store_dwordx4 v130, v[100:103], s[10:11] nt
	s_nop 1
	v_cvt_pk_f16_f32 v100, v100, v101
	v_cvt_pk_f16_f32 v101, v102, v103
	global_store_dwordx2 v128, v[100:101], s[4:5]
	global_store_dwordx4 v130, v[68:71], s[10:11] offset:64 nt
	s_nop 1
	v_cvt_pk_f16_f32 v68, v68, v69
	v_cvt_pk_f16_f32 v69, v70, v71
	global_store_dwordx2 v128, v[68:69], s[4:5] offset:32
	global_store_dwordx4 v130, v[36:39], s[10:11] offset:128 nt
	s_nop 1
	v_cvt_pk_f16_f32 v36, v36, v37
	v_cvt_pk_f16_f32 v37, v38, v39
	global_store_dwordx2 v128, v[36:37], s[4:5] offset:64
	global_store_dwordx4 v130, v[4:7], s[10:11] offset:192 nt
	s_nop 1
	v_cvt_pk_f16_f32 v4, v4, v5
	v_cvt_pk_f16_f32 v5, v6, v7
	global_store_dwordx2 v128, v[4:5], s[4:5] offset:96
	s_add_u32 s4, s4, 0x30200
	s_addc_u32 s5, s5, 0
	s_add_u32 s10, s10, s18
	s_addc_u32 s11, s11, 0
	global_store_dwordx4 v130, v[96:99], s[10:11] nt
	s_nop 1
	v_cvt_pk_f16_f32 v96, v96, v97
	v_cvt_pk_f16_f32 v97, v98, v99
	global_store_dwordx2 v128, v[96:97], s[4:5]
	global_store_dwordx4 v130, v[64:67], s[10:11] offset:64 nt
	s_nop 1
	v_cvt_pk_f16_f32 v64, v64, v65
	v_cvt_pk_f16_f32 v65, v66, v67
	global_store_dwordx2 v128, v[64:65], s[4:5] offset:32
	global_store_dwordx4 v130, v[32:35], s[10:11] offset:128 nt
	s_nop 1
	v_cvt_pk_f16_f32 v32, v32, v33
	v_cvt_pk_f16_f32 v33, v34, v35
	global_store_dwordx2 v128, v[32:33], s[4:5] offset:64
	global_store_dwordx4 v130, v[0:3], s[10:11] offset:192 nt
	s_nop 1
	v_cvt_pk_f16_f32 v0, v0, v1
	v_cvt_pk_f16_f32 v1, v2, v3
	global_store_dwordx2 v128, v[0:1], s[4:5] offset:96
	s_mov_b64 s[50:51], exec
	s_branch .LBB0_315
.Lgin_notplain:
	s_cmpk_lt_u32 s9, 0x620
	s_cselect_b64 s[44:45], -1, 0
	s_cmpk_gt_u32 s9, 0x61f
	s_cselect_b64 s[4:5], -1, 0
	s_cmp_lt_u32 s16, 6
	s_cselect_b64 s[6:7], -1, 0
	s_and_b64 s[4:5], s[4:5], s[6:7]
	s_and_b64 vcc, exec, s[4:5]
	s_cbranch_vccz .LBB0_320
	v_add_u32_e32 v128, s8, v174
	s_movk_i32 s4, 0x380
	v_and_or_b32 v128, v128, s4, v166
	v_readlane_b32 s4, v254, 41
	v_lshl_or_b32 v168, v128, 9, v180
	v_readlane_b32 s5, v254, 42
	s_nop 4
	global_load_dwordx4 v[130:133], v168, s[4:5] offset:16
	global_load_dwordx4 v[152:155], v168, s[4:5]
	v_lshl_add_u64 v[128:129], s[4:5], 0, v[168:169]
	s_waitcnt vmcnt(1)
	v_mul_f32_e32 v158, v62, v131
	s_waitcnt vmcnt(0)
	v_mov_b32_e32 v150, v153
	v_mov_b32_e32 v153, v154
	v_mul_f32_e32 v154, v126, v130
	v_mul_f32_e32 v160, v126, v131
	v_mul_f32_e32 v130, v62, v130
	v_mov_b32_e32 v62, v127
	v_mov_b32_e32 v126, v63
	v_mov_b32_e32 v151, v155
	v_pk_mul_f32 v[162:163], v[62:63], v[132:133]
	v_pk_mul_f32 v[62:63], v[126:127], v[132:133]
	v_pk_mul_f32 v[156:157], v[124:125], v[150:151]
	v_pk_mul_f32 v[150:151], v[60:61], v[150:151]
	v_mov_b32_e32 v155, v162
	v_mov_b32_e32 v159, v163
	v_mov_b32_e32 v131, v62
	v_mov_b32_e32 v161, v63
	v_pk_fma_f32 v[124:125], v[124:125], v[152:153], v[150:151] neg_lo:[0,0,1] neg_hi:[0,0,1]
	v_pk_add_f32 v[150:151], v[154:155], v[158:159] neg_lo:[0,1] neg_hi:[0,1]
	v_pk_fma_f32 v[60:61], v[60:61], v[152:153], v[156:157]
	v_pk_add_f32 v[62:63], v[130:131], v[160:161]
	global_load_dwordx4 v[130:133], v168, s[4:5] offset:144
	global_load_dwordx4 v[154:157], v168, s[4:5] offset:128
	s_mov_b64 s[4:5], 0x2080
	s_waitcnt vmcnt(1)
	v_mul_f32_e32 v152, v94, v130
	s_waitcnt vmcnt(0)
	v_mov_b32_e32 v126, v155
	v_mov_b32_e32 v127, v157
	v_pk_mul_f32 v[158:159], v[92:93], v[126:127]
	v_mov_b32_e32 v155, v156
	v_pk_mul_f32 v[126:127], v[28:29], v[126:127]
	v_mul_f32_e32 v156, v30, v131
	v_mul_f32_e32 v160, v94, v131
	v_mul_f32_e32 v130, v30, v130
	v_mov_b32_e32 v30, v95
	v_mov_b32_e32 v94, v31
	v_pk_mul_f32 v[162:163], v[30:31], v[132:133]
	v_pk_fma_f32 v[92:93], v[92:93], v[154:155], v[126:127] neg_lo:[0,0,1] neg_hi:[0,0,1]
	v_pk_mul_f32 v[30:31], v[94:95], v[132:133]
	v_add_co_u32_e32 v126, vcc, s33, v128
	v_mov_b32_e32 v153, v162
	v_mov_b32_e32 v157, v163
	v_mov_b32_e32 v131, v30
	v_mov_b32_e32 v161, v31
	v_addc_co_u32_e32 v127, vcc, 0, v129, vcc
	v_pk_add_f32 v[152:153], v[152:153], v[156:157] neg_lo:[0,1] neg_hi:[0,1]
	v_pk_fma_f32 v[28:29], v[28:29], v[154:155], v[158:159]
	v_pk_add_f32 v[30:31], v[130:131], v[160:161]
	v_lshl_add_u64 v[94:95], v[128:129], 0, s[26:27]
	global_load_dwordx4 v[130:133], v[126:127], off
	global_load_dwordx4 v[154:157], v[94:95], off offset:16
	s_waitcnt vmcnt(1)
	v_mov_b32_e32 v94, v131
	s_waitcnt vmcnt(0)
	v_mul_f32_e32 v160, v58, v155
	v_mul_f32_e32 v164, v58, v154
	v_mov_b32_e32 v58, v123
	v_mov_b32_e32 v95, v133
	v_mov_b32_e32 v131, v132
	v_mul_f32_e32 v132, v122, v154
	v_mul_f32_e32 v162, v122, v155
	v_pk_mul_f32 v[154:155], v[58:59], v[156:157]
	v_pk_mul_f32 v[158:159], v[120:121], v[94:95]
	v_pk_mul_f32 v[94:95], v[56:57], v[94:95]
	v_mov_b32_e32 v133, v154
	v_mov_b32_e32 v161, v155
	v_mov_b32_e32 v122, v59
	v_pk_fma_f32 v[120:121], v[120:121], v[130:131], v[94:95] neg_lo:[0,0,1] neg_hi:[0,0,1]
	v_pk_add_f32 v[154:155], v[132:133], v[160:161] neg_lo:[0,1] neg_hi:[0,1]
	v_pk_mul_f32 v[58:59], v[122:123], v[156:157]
	v_pk_fma_f32 v[56:57], v[56:57], v[130:131], v[158:159]
	v_lshl_add_u64 v[94:95], v[128:129], 0, s[4:5]
	global_load_dwordx4 v[130:133], v[126:127], off offset:128
	global_load_dwordx4 v[156:159], v[94:95], off offset:16
	v_mov_b32_e32 v165, v58
	v_mov_b32_e32 v163, v59
	v_pk_add_f32 v[58:59], v[164:165], v[162:163]
	s_mov_b64 s[4:5], 0x4080
	s_waitcnt vmcnt(1)
	v_mov_b32_e32 v94, v131
	v_mov_b32_e32 v131, v132
	s_waitcnt vmcnt(0)
	v_mul_f32_e32 v126, v90, v156
	v_mul_f32_e32 v132, v26, v157
	v_mul_f32_e32 v160, v90, v157
	v_mul_f32_e32 v156, v26, v156
	v_mov_b32_e32 v26, v91
	v_mov_b32_e32 v90, v27
	v_mov_b32_e32 v95, v133
	v_pk_mul_f32 v[162:163], v[26:27], v[158:159]
	v_pk_mul_f32 v[26:27], v[90:91], v[158:159]
	v_add_co_u32_e32 v90, vcc, s97, v128
	v_pk_mul_f32 v[122:123], v[88:89], v[94:95]
	v_pk_mul_f32 v[94:95], v[24:25], v[94:95]
	v_mov_b32_e32 v127, v162
	v_mov_b32_e32 v133, v163
	v_mov_b32_e32 v157, v26
	v_mov_b32_e32 v161, v27
	v_addc_co_u32_e32 v91, vcc, 0, v129, vcc
	v_pk_fma_f32 v[88:89], v[88:89], v[130:131], v[94:95] neg_lo:[0,0,1] neg_hi:[0,0,1]
	v_pk_add_f32 v[94:95], v[126:127], v[132:133] neg_lo:[0,1] neg_hi:[0,1]
	v_pk_fma_f32 v[24:25], v[24:25], v[130:131], v[122:123]
	v_pk_add_f32 v[26:27], v[156:157], v[160:161]
	v_lshl_add_u64 v[122:123], v[128:129], 0, s[84:85]
	global_load_dwordx4 v[130:133], v[90:91], off
	global_load_dwordx4 v[156:159], v[122:123], off offset:16
	s_waitcnt vmcnt(1)
	v_mov_b32_e32 v122, v131
	v_mov_b32_e32 v131, v132
	s_waitcnt vmcnt(0)
	v_mul_f32_e32 v132, v118, v156
	v_mul_f32_e32 v160, v54, v157
	v_mul_f32_e32 v162, v118, v157
	v_mul_f32_e32 v156, v54, v156
	v_mov_b32_e32 v54, v119
	v_mov_b32_e32 v118, v55
	v_mov_b32_e32 v123, v133
	v_pk_mul_f32 v[164:165], v[54:55], v[158:159]
	v_pk_mul_f32 v[54:55], v[118:119], v[158:159]
	v_pk_mul_f32 v[126:127], v[116:117], v[122:123]
	v_pk_mul_f32 v[122:123], v[52:53], v[122:123]
	v_mov_b32_e32 v133, v164
	v_mov_b32_e32 v161, v165
	v_mov_b32_e32 v157, v54
	v_mov_b32_e32 v163, v55
	v_pk_fma_f32 v[116:117], v[116:117], v[130:131], v[122:123] neg_lo:[0,0,1] neg_hi:[0,0,1]
	v_pk_add_f32 v[122:123], v[132:133], v[160:161] neg_lo:[0,1] neg_hi:[0,1]
	v_pk_fma_f32 v[52:53], v[52:53], v[130:131], v[126:127]
	v_pk_add_f32 v[54:55], v[156:157], v[162:163]
	v_lshl_add_u64 v[118:119], v[128:129], 0, s[4:5]
	global_load_dwordx4 v[130:133], v[90:91], off offset:128
	global_load_dwordx4 v[156:159], v[118:119], off offset:16
	s_mov_b64 s[4:5], 0x6080
	s_waitcnt vmcnt(1)
	v_mov_b32_e32 v90, v131
	v_mov_b32_e32 v131, v132
	s_waitcnt vmcnt(0)
	v_mul_f32_e32 v126, v86, v156
	v_mul_f32_e32 v132, v22, v157
	v_mul_f32_e32 v156, v22, v156
	v_mov_b32_e32 v22, v87
	v_mov_b32_e32 v91, v133
	v_pk_mul_f32 v[162:163], v[22:23], v[158:159]
	v_pk_mul_f32 v[118:119], v[84:85], v[90:91]
	v_pk_mul_f32 v[90:91], v[20:21], v[90:91]
	v_mul_f32_e32 v160, v86, v157
	v_mov_b32_e32 v127, v162
	v_mov_b32_e32 v133, v163
	v_mov_b32_e32 v86, v23
	v_pk_fma_f32 v[84:85], v[84:85], v[130:131], v[90:91] neg_lo:[0,0,1] neg_hi:[0,0,1]
	v_pk_add_f32 v[90:91], v[126:127], v[132:133] neg_lo:[0,1] neg_hi:[0,1]
	v_pk_mul_f32 v[22:23], v[86:87], v[158:159]
	v_add_co_u32_e32 v126, vcc, s24, v128
	v_mov_b32_e32 v157, v22
	v_mov_b32_e32 v161, v23
	v_addc_co_u32_e32 v127, vcc, 0, v129, vcc
	v_pk_fma_f32 v[20:21], v[20:21], v[130:131], v[118:119]
	v_pk_add_f32 v[22:23], v[156:157], v[160:161]
	v_lshl_add_u64 v[86:87], v[128:129], 0, s[28:29]
	global_load_dwordx4 v[130:133], v[126:127], off
	global_load_dwordx4 v[156:159], v[86:87], off offset:16
	s_waitcnt vmcnt(1)
	v_mov_b32_e32 v86, v131
	v_mov_b32_e32 v131, v132
	s_waitcnt vmcnt(0)
	v_mul_f32_e32 v118, v114, v156
	v_mul_f32_e32 v132, v50, v157
	v_mul_f32_e32 v162, v114, v157
	v_mul_f32_e32 v156, v50, v156
	v_mov_b32_e32 v50, v115
	v_mov_b32_e32 v114, v51
	v_mov_b32_e32 v87, v133
	v_pk_mul_f32 v[164:165], v[50:51], v[158:159]
	v_pk_mul_f32 v[50:51], v[114:115], v[158:159]
	v_pk_mul_f32 v[160:161], v[112:113], v[86:87]
	v_pk_mul_f32 v[86:87], v[48:49], v[86:87]
	v_mov_b32_e32 v119, v164
	v_mov_b32_e32 v133, v165
	v_mov_b32_e32 v157, v50
	v_mov_b32_e32 v163, v51
	v_pk_fma_f32 v[112:113], v[112:113], v[130:131], v[86:87] neg_lo:[0,0,1] neg_hi:[0,0,1]
	v_pk_add_f32 v[118:119], v[118:119], v[132:133] neg_lo:[0,1] neg_hi:[0,1]
	v_pk_fma_f32 v[48:49], v[48:49], v[130:131], v[160:161]
	v_pk_add_f32 v[50:51], v[156:157], v[162:163]
	v_lshl_add_u64 v[86:87], v[128:129], 0, s[4:5]
	global_load_dwordx4 v[130:133], v[126:127], off offset:128
	global_load_dwordx4 v[156:159], v[86:87], off offset:16
	s_mov_b64 s[4:5], 0x8000
	s_waitcnt vmcnt(1)
	v_mov_b32_e32 v86, v131
	v_mov_b32_e32 v131, v132
	s_waitcnt vmcnt(0)
	v_mul_f32_e32 v126, v82, v156
	v_mul_f32_e32 v132, v18, v157
	v_mul_f32_e32 v156, v18, v156
	v_mov_b32_e32 v18, v83
	v_mov_b32_e32 v87, v133
	v_mul_f32_e32 v160, v82, v157
	v_pk_mul_f32 v[162:163], v[18:19], v[158:159]
	v_mov_b32_e32 v82, v19
	v_pk_mul_f32 v[114:115], v[80:81], v[86:87]
	v_pk_mul_f32 v[86:87], v[16:17], v[86:87]
	v_mov_b32_e32 v127, v162
	v_mov_b32_e32 v133, v163
	v_pk_mul_f32 v[18:19], v[82:83], v[158:159]
	v_lshl_add_u64 v[82:83], v[128:129], 0, s[4:5]
	s_mov_b32 s4, 0x8000
	v_pk_fma_f32 v[80:81], v[80:81], v[130:131], v[86:87] neg_lo:[0,0,1] neg_hi:[0,0,1]
	v_pk_add_f32 v[86:87], v[126:127], v[132:133] neg_lo:[0,1] neg_hi:[0,1]
	v_add_co_u32_e32 v126, vcc, s4, v128
	v_mov_b32_e32 v157, v18
	v_mov_b32_e32 v161, v19
	v_addc_co_u32_e32 v127, vcc, 0, v129, vcc
	v_pk_fma_f32 v[16:17], v[16:17], v[130:131], v[114:115]
	v_pk_add_f32 v[18:19], v[156:157], v[160:161]
	global_load_dwordx4 v[130:133], v[126:127], off
	global_load_dwordx4 v[156:159], v[82:83], off offset:16
	s_mov_b64 s[4:5], 0x8080
	s_waitcnt vmcnt(1)
	v_mov_b32_e32 v82, v131
	v_mov_b32_e32 v131, v132
	s_waitcnt vmcnt(0)
	v_mul_f32_e32 v114, v110, v156
	v_mul_f32_e32 v132, v46, v157
	v_mul_f32_e32 v162, v110, v157
	v_mul_f32_e32 v156, v46, v156
	v_mov_b32_e32 v46, v111
	v_mov_b32_e32 v110, v47
	v_mov_b32_e32 v83, v133
	v_pk_mul_f32 v[164:165], v[46:47], v[158:159]
	v_pk_mul_f32 v[46:47], v[110:111], v[158:159]
	v_pk_mul_f32 v[160:161], v[108:109], v[82:83]
	v_pk_mul_f32 v[82:83], v[44:45], v[82:83]
	v_mov_b32_e32 v115, v164
	v_mov_b32_e32 v133, v165
	v_mov_b32_e32 v157, v46
	v_mov_b32_e32 v163, v47
	v_pk_fma_f32 v[108:109], v[108:109], v[130:131], v[82:83] neg_lo:[0,0,1] neg_hi:[0,0,1]
	v_pk_add_f32 v[114:115], v[114:115], v[132:133] neg_lo:[0,1] neg_hi:[0,1]
	v_pk_fma_f32 v[44:45], v[44:45], v[130:131], v[160:161]
	v_pk_add_f32 v[46:47], v[156:157], v[162:163]
	v_lshl_add_u64 v[82:83], v[128:129], 0, s[4:5]
	global_load_dwordx4 v[130:133], v[126:127], off offset:128
	global_load_dwordx4 v[156:159], v[82:83], off offset:16
	s_mov_b64 s[4:5], 0xa000
	s_waitcnt vmcnt(1)
	v_mov_b32_e32 v82, v131
	v_mov_b32_e32 v131, v132
	s_waitcnt vmcnt(0)
	v_mul_f32_e32 v126, v78, v156
	v_mul_f32_e32 v132, v14, v157
	v_mul_f32_e32 v156, v14, v156
	v_mov_b32_e32 v14, v79
	v_mov_b32_e32 v83, v133
	v_mul_f32_e32 v160, v78, v157
	v_pk_mul_f32 v[162:163], v[14:15], v[158:159]
	v_mov_b32_e32 v78, v15
	v_pk_mul_f32 v[110:111], v[76:77], v[82:83]
	v_pk_mul_f32 v[82:83], v[12:13], v[82:83]
	v_mov_b32_e32 v127, v162
	v_mov_b32_e32 v133, v163
	v_pk_mul_f32 v[14:15], v[78:79], v[158:159]
	v_lshl_add_u64 v[78:79], v[128:129], 0, s[4:5]
	s_mov_b32 s4, 0xa000
	v_pk_fma_f32 v[76:77], v[76:77], v[130:131], v[82:83] neg_lo:[0,0,1] neg_hi:[0,0,1]
	v_pk_add_f32 v[82:83], v[126:127], v[132:133] neg_lo:[0,1] neg_hi:[0,1]
	v_add_co_u32_e32 v126, vcc, s4, v128
	v_mov_b32_e32 v157, v14
	v_mov_b32_e32 v161, v15
	v_addc_co_u32_e32 v127, vcc, 0, v129, vcc
	v_pk_fma_f32 v[12:13], v[12:13], v[130:131], v[110:111]
	v_pk_add_f32 v[14:15], v[156:157], v[160:161]
	global_load_dwordx4 v[130:133], v[126:127], off
	global_load_dwordx4 v[156:159], v[78:79], off offset:16
	s_mov_b64 s[4:5], 0xa080
	s_waitcnt vmcnt(1)
	v_mov_b32_e32 v78, v131
	v_mov_b32_e32 v131, v132
	s_waitcnt vmcnt(0)
	v_mul_f32_e32 v110, v106, v156
	v_mul_f32_e32 v132, v42, v157
	v_mul_f32_e32 v162, v106, v157
	v_mul_f32_e32 v156, v42, v156
	v_mov_b32_e32 v42, v107
	v_mov_b32_e32 v106, v43
	v_mov_b32_e32 v79, v133
	v_pk_mul_f32 v[164:165], v[42:43], v[158:159]
	v_pk_mul_f32 v[42:43], v[106:107], v[158:159]
	v_pk_mul_f32 v[160:161], v[104:105], v[78:79]
	v_pk_mul_f32 v[78:79], v[40:41], v[78:79]
	v_mov_b32_e32 v111, v164
	v_mov_b32_e32 v133, v165
	v_mov_b32_e32 v157, v42
	v_mov_b32_e32 v163, v43
	v_pk_fma_f32 v[104:105], v[104:105], v[130:131], v[78:79] neg_lo:[0,0,1] neg_hi:[0,0,1]
	v_pk_add_f32 v[110:111], v[110:111], v[132:133] neg_lo:[0,1] neg_hi:[0,1]
	v_pk_fma_f32 v[40:41], v[40:41], v[130:131], v[160:161]
	v_pk_add_f32 v[42:43], v[156:157], v[162:163]
	v_lshl_add_u64 v[78:79], v[128:129], 0, s[4:5]
	global_load_dwordx4 v[130:133], v[126:127], off offset:128
	global_load_dwordx4 v[156:159], v[78:79], off offset:16
	s_mov_b64 s[4:5], 0xc000
	s_waitcnt vmcnt(1)
	v_mov_b32_e32 v78, v131
	v_mov_b32_e32 v131, v132
	s_waitcnt vmcnt(0)
	v_mul_f32_e32 v126, v74, v156
	v_mul_f32_e32 v132, v10, v157
	v_mul_f32_e32 v156, v10, v156
	v_mov_b32_e32 v10, v75
	v_mov_b32_e32 v79, v133
	v_mul_f32_e32 v160, v74, v157
	v_pk_mul_f32 v[162:163], v[10:11], v[158:159]
	v_mov_b32_e32 v74, v11
	v_pk_mul_f32 v[106:107], v[72:73], v[78:79]
	v_pk_mul_f32 v[78:79], v[8:9], v[78:79]
	v_mov_b32_e32 v127, v162
	v_mov_b32_e32 v133, v163
	v_pk_mul_f32 v[10:11], v[74:75], v[158:159]
	v_lshl_add_u64 v[74:75], v[128:129], 0, s[4:5]
	s_mov_b32 s4, 0xc000
	v_pk_fma_f32 v[72:73], v[72:73], v[130:131], v[78:79] neg_lo:[0,0,1] neg_hi:[0,0,1]
	v_pk_add_f32 v[78:79], v[126:127], v[132:133] neg_lo:[0,1] neg_hi:[0,1]
	v_add_co_u32_e32 v126, vcc, s4, v128
	v_mov_b32_e32 v157, v10
	v_mov_b32_e32 v161, v11
	v_addc_co_u32_e32 v127, vcc, 0, v129, vcc
	v_pk_fma_f32 v[8:9], v[8:9], v[130:131], v[106:107]
	v_pk_add_f32 v[10:11], v[156:157], v[160:161]
	global_load_dwordx4 v[130:133], v[126:127], off
	global_load_dwordx4 v[156:159], v[74:75], off offset:16
	s_mov_b64 s[4:5], 0xc080
	s_waitcnt vmcnt(1)
	v_mov_b32_e32 v74, v131
	v_mov_b32_e32 v131, v132
	s_waitcnt vmcnt(0)
	v_mul_f32_e32 v106, v102, v156
	v_mul_f32_e32 v132, v38, v157
	v_mul_f32_e32 v162, v102, v157
	v_mul_f32_e32 v156, v38, v156
	v_mov_b32_e32 v38, v103
	v_mov_b32_e32 v102, v39
	v_mov_b32_e32 v75, v133
	v_pk_mul_f32 v[164:165], v[38:39], v[158:159]
	v_pk_mul_f32 v[38:39], v[102:103], v[158:159]
	v_pk_mul_f32 v[160:161], v[100:101], v[74:75]
	v_pk_mul_f32 v[74:75], v[36:37], v[74:75]
	v_mov_b32_e32 v107, v164
	v_mov_b32_e32 v133, v165
	v_mov_b32_e32 v157, v38
	v_mov_b32_e32 v163, v39
	v_pk_fma_f32 v[100:101], v[100:101], v[130:131], v[74:75] neg_lo:[0,0,1] neg_hi:[0,0,1]
	v_pk_add_f32 v[106:107], v[106:107], v[132:133] neg_lo:[0,1] neg_hi:[0,1]
	v_pk_fma_f32 v[36:37], v[36:37], v[130:131], v[160:161]
	v_pk_add_f32 v[38:39], v[156:157], v[162:163]
	v_lshl_add_u64 v[74:75], v[128:129], 0, s[4:5]
	global_load_dwordx4 v[130:133], v[126:127], off offset:128
	global_load_dwordx4 v[156:159], v[74:75], off offset:16
	s_mov_b64 s[4:5], 0xe000
	s_waitcnt vmcnt(1)
	v_mov_b32_e32 v74, v131
	v_mov_b32_e32 v131, v132
	s_waitcnt vmcnt(0)
	v_mul_f32_e32 v126, v70, v156
	v_mul_f32_e32 v132, v6, v157
	v_mul_f32_e32 v156, v6, v156
	v_mov_b32_e32 v6, v71
	v_mov_b32_e32 v75, v133
	v_mul_f32_e32 v160, v70, v157
	v_pk_mul_f32 v[162:163], v[6:7], v[158:159]
	v_mov_b32_e32 v70, v7
	v_pk_mul_f32 v[102:103], v[68:69], v[74:75]
	v_pk_mul_f32 v[74:75], v[4:5], v[74:75]
	v_mov_b32_e32 v127, v162
	v_mov_b32_e32 v133, v163
	v_pk_mul_f32 v[6:7], v[70:71], v[158:159]
	v_lshl_add_u64 v[70:71], v[128:129], 0, s[4:5]
	s_mov_b32 s4, 0xe000
	v_pk_fma_f32 v[68:69], v[68:69], v[130:131], v[74:75] neg_lo:[0,0,1] neg_hi:[0,0,1]
	v_pk_add_f32 v[74:75], v[126:127], v[132:133] neg_lo:[0,1] neg_hi:[0,1]
	v_add_co_u32_e32 v126, vcc, s4, v128
	v_mov_b32_e32 v157, v6
	v_mov_b32_e32 v161, v7
	v_addc_co_u32_e32 v127, vcc, 0, v129, vcc
	v_pk_fma_f32 v[4:5], v[4:5], v[130:131], v[102:103]
	v_pk_add_f32 v[6:7], v[156:157], v[160:161]
	global_load_dwordx4 v[130:133], v[126:127], off
	global_load_dwordx4 v[156:159], v[70:71], off offset:16
	s_mov_b64 s[4:5], 0xe080
	s_waitcnt vmcnt(1)
	v_mov_b32_e32 v70, v131
	v_mov_b32_e32 v131, v132
	s_waitcnt vmcnt(0)
	v_mul_f32_e32 v102, v98, v156
	v_mul_f32_e32 v132, v34, v157
	v_mul_f32_e32 v156, v34, v156
	v_mov_b32_e32 v34, v99
	v_mov_b32_e32 v71, v133
	v_pk_mul_f32 v[164:165], v[34:35], v[158:159]
	v_pk_mul_f32 v[160:161], v[96:97], v[70:71]
	v_pk_mul_f32 v[70:71], v[32:33], v[70:71]
	v_mov_b32_e32 v103, v164
	v_mov_b32_e32 v133, v165
	v_pk_fma_f32 v[96:97], v[96:97], v[130:131], v[70:71] neg_lo:[0,0,1] neg_hi:[0,0,1]
	v_pk_add_f32 v[102:103], v[102:103], v[132:133] neg_lo:[0,1] neg_hi:[0,1]
	v_pk_fma_f32 v[32:33], v[32:33], v[130:131], v[160:161]
	v_lshl_add_u64 v[70:71], v[128:129], 0, s[4:5]
	global_load_dwordx4 v[126:129], v[126:127], off offset:128
	s_nop 0
	global_load_dwordx4 v[130:133], v[70:71], off offset:16
	v_mul_f32_e32 v162, v98, v157
	v_mov_b32_e32 v98, v35
	v_pk_mul_f32 v[34:35], v[98:99], v[158:159]
	s_waitcnt vmcnt(1)
	v_mov_b32_e32 v70, v127
	v_mov_b32_e32 v157, v34
	v_mov_b32_e32 v163, v35
	v_pk_add_f32 v[34:35], v[156:157], v[162:163]
	v_mov_b32_e32 v127, v128
	s_waitcnt vmcnt(0)
	v_mul_f32_e32 v128, v66, v130
	v_mul_f32_e32 v156, v2, v131
	v_mul_f32_e32 v130, v2, v130
	v_mov_b32_e32 v2, v67
	v_mov_b32_e32 v71, v129
	v_mul_f32_e32 v158, v66, v131
	v_pk_mul_f32 v[160:161], v[2:3], v[132:133]
	v_mov_b32_e32 v66, v3
	v_pk_mul_f32 v[98:99], v[64:65], v[70:71]
	v_pk_mul_f32 v[70:71], v[0:1], v[70:71]
	v_mov_b32_e32 v129, v160
	v_mov_b32_e32 v157, v161
	v_pk_mul_f32 v[2:3], v[66:67], v[132:133]
	v_pk_fma_f32 v[64:65], v[64:65], v[126:127], v[70:71] neg_lo:[0,0,1] neg_hi:[0,0,1]
	v_pk_add_f32 v[70:71], v[128:129], v[156:157] neg_lo:[0,1] neg_hi:[0,1]
	v_mov_b32_e32 v131, v2
	v_mov_b32_e32 v159, v3
	v_pk_fma_f32 v[0:1], v[0:1], v[126:127], v[98:99]
	v_pk_add_f32 v[2:3], v[130:131], v[158:159]
	v_mov_b32_e32 v66, v70
	v_mov_b32_e32 v67, v71
	v_mov_b32_e32 v70, v74
	v_mov_b32_e32 v71, v75
	v_mov_b32_e32 v74, v78
	v_mov_b32_e32 v75, v79
	v_mov_b32_e32 v78, v82
	v_mov_b32_e32 v79, v83
	v_mov_b32_e32 v82, v86
	v_mov_b32_e32 v83, v87
	v_mov_b32_e32 v86, v90
	v_mov_b32_e32 v87, v91
	v_mov_b32_e32 v90, v94
	v_mov_b32_e32 v91, v95
	v_mov_b32_e32 v94, v152
	v_mov_b32_e32 v95, v153
	v_mov_b32_e32 v98, v102
	v_mov_b32_e32 v99, v103
	v_mov_b32_e32 v102, v106
	v_mov_b32_e32 v103, v107
	v_mov_b32_e32 v106, v110
	v_mov_b32_e32 v107, v111
	v_mov_b32_e32 v110, v114
	v_mov_b32_e32 v111, v115
	v_mov_b32_e32 v114, v118
	v_mov_b32_e32 v115, v119
	v_mov_b32_e32 v118, v122
	v_mov_b32_e32 v119, v123
	v_mov_b32_e32 v122, v154
	v_mov_b32_e32 v123, v155
	v_mov_b32_e32 v126, v150
	v_mov_b32_e32 v127, v151
